# GEMM: peel first K-iteration per tile (first MFMA per accumulator uses C=0), drop 128 v_mov accumulator zeroing
# speedup vs baseline: 1.0139x; 1.0059x over previous
; #define PG8_STAGE(bufoff, gbase, voff) do { _Pragma("unroll") for (int _i = 0; _i < 2; ++_i) \
;         __builtin_amdgcn_global_load_lds((const unsigned*)((const char*)(gbase) + (voff)[_i]), (LAS unsigned*)(lds + (bufoff) + ldsw + _i * 8192), 16, 0, 0); } while (0)
; #define PG8_LDA(dst, b, h) do { _Pragma("unroll") for (int m = 0; m < 4; ++m) _Pragma("unroll") for (int k = 0; k < 2; ++k) dst[m][k] = *(const LAS bf16x8*)(lds + PG8_SA(b, h) + aoff + m * 2048 + k * 1024); } while (0)
; #define PG8_LDB(dst, b, h) do { _Pragma("unroll") for (int n = 0; n < 2; ++n) _Pragma("unroll") for (int k = 0; k < 2; ++k) dst[n][k] = *(const LAS bf16x8*)(lds + PG8_SB(b, h) + boff + n * 2048 + k * 1024); } while (0)
; #define PG8_MMA(ai, bj, At, Bt) do { __builtin_amdgcn_s_setprio(1); _Pragma("unroll") for (int m = 0; m < 4; ++m) _Pragma("unroll") for (int n = 0; n < 2; ++n) _Pragma("unroll") for (int k = 0; k < 2; ++k) \
;         acc[ai][bj][m][n] = __builtin_amdgcn_mfma_f32_16x16x32_bf16(Bt[n][k], At[m][k], acc[ai][bj][m][n], 0, 0, 0); __builtin_amdgcn_s_setprio(0); } while (0)
; #define PG8_WAIT_L(n) asm volatile("s_waitcnt lgkmcnt(" #n ")" ::: "memory")
; template <class Epi>
; __device__ __forceinline__ void gemm_phase(LAS unsigned char* lds, const Gemm g, const StaticOrder& S, const Epi& E) {
;     ...
;         const bool has_next = S.next(ui + 1, nxt);
;         const char* nA = has_next ? (const char*)g.A + (size_t)nxt.pm * tstepA : cA; const char* nB = has_next ? (const char*)g.Bt + (size_t)nxt.pn * tstepB : cB;
;         for (int t = 0; t < nt; t += 2) {
;             const bool last = (t == nt - 2);
;             const char* a1 = cA + (size_t)(t + 1) * kstep;
;             const char* a2 = last ? nA : cA + (size_t)(t + 2) * kstep; const char* b2 = last ? nB : cB + (size_t)(t + 2) * kstep;
;             const char* a3 = a2 + kstep; const char* b3 = b2 + kstep;
;             PG8_LDB(B0, 0, 0); PG8_SCHED; PG8_LDA(At, 0, 0); PG8_STAGE(PG8_SA(1, 1), a1 + hstepA, voffA);
;             PG8_WAIT_L(8); PG8_BAR; PG8_WAIT_L(0); PG8_MMA(0, 0, At, B0); PG8_BAR; PG8_SCHED;
;             PG8_LDB(B1, 0, 1); PG8_STAGE(PG8_SB(0, 0), b2, voffB);
;             PG8_BAR; PG8_WAIT_L(0); PG8_MMA(0, 1, At, B1); PG8_BAR;
;             PG8_LDA(At, 0, 1); PG8_STAGE(PG8_SA(0, 0), a2, voffA);
;             PG8_BAR; PG8_WAIT_L(0); PG8_MMA(1, 0, At, B0); PG8_BAR; PG8_SCHED;
.LBB0_140:
	v_mov_b64_e32 v[0:1], 0x800
	s_ashr_i32 s15, s14, 31
	v_cmp_lt_i64_e32 vcc, s[16:17], v[0:1]
	s_lshl_b64 s[16:17], s[14:15], 20
	v_readlane_b32 s18, v252, 53
	v_readlane_b32 s19, v252, 54
	s_add_u32 s16, s18, s16
	s_addc_u32 s17, s19, s17
	s_and_b64 s[18:19], vcc, exec
	s_cselect_b32 s15, s17, s23
	s_cselect_b32 s49, s16, s22
	s_ashr_i32 s5, s4, 31
	s_lshl_b64 s[18:19], s[4:5], 20
	s_add_u32 s18, s34, s18
	s_addc_u32 s19, s35, s19
	s_and_b64 s[26:27], vcc, exec
	s_cselect_b32 s5, s19, s25
	s_cselect_b32 s50, s18, s24
	s_add_u32 s22, s22, 0x84000
	s_addc_u32 s23, s23, 0
	s_add_u32 s51, s24, 0x8000
	s_addc_u32 s52, s25, 0
	s_mov_b32 s54, -2
	s_add_u32 s24, s22, 0xfff84000
	s_addc_u32 s25, s23, -1
	s_cmp_eq_u32 s54, 28
	s_cselect_b32 s28, s49, s24
	s_cselect_b32 s29, s15, s25
	s_cselect_b32 s24, s50, s51
	s_cselect_b32 s25, s5, s52
	s_add_u32 s26, s28, 0x4000
	s_addc_u32 s27, s29, 0
	s_add_i32 s55, 0, 0x10000
	v_add_u32_e32 v148, s55, v134
	ds_read_b128 v[136:139], v148
	ds_read_b128 v[140:143], v148 offset:1024
	ds_read_b128 v[144:147], v148 offset:2048
	ds_read_b128 v[148:151], v148 offset:3072
	v_lshl_add_u64 v[188:189], s[22:23], 0, v[128:129]
	s_add_i32 m0, s37, 0xc000
	ds_read_b128 v[156:159], v135
	ds_read_b128 v[160:163], v135 offset:1024
	ds_read_b128 v[164:167], v135 offset:2048
	ds_read_b128 v[168:171], v135 offset:3072
	ds_read_b128 v[172:175], v135 offset:4096
	ds_read_b128 v[176:179], v135 offset:5120
	ds_read_b128 v[180:183], v135 offset:6144
	ds_read_b128 v[184:187], v135 offset:7168
	global_load_lds_dwordx4 v[188:189], off
	s_add_i32 m0, s37, 0xe000
	v_lshl_add_u64 v[188:189], s[22:23], 0, v[130:131]
	global_load_lds_dwordx4 v[188:189], off
	s_waitcnt lgkmcnt(8)
	s_barrier
	s_waitcnt lgkmcnt(0)
	v_mfma_f32_16x16x32_bf16 v[124:127], v[136:139], v[156:159], 0
	s_setprio 1
	v_mfma_f32_16x16x32_bf16 v[120:123], v[144:147], v[156:159], 0
	v_mfma_f32_16x16x32_bf16 v[108:111], v[136:139], v[164:167], 0
	v_mfma_f32_16x16x32_bf16 v[104:107], v[144:147], v[164:167], 0
	v_mfma_f32_16x16x32_bf16 v[92:95], v[136:139], v[172:175], 0
	v_mfma_f32_16x16x32_bf16 v[88:91], v[144:147], v[172:175], 0
	v_mfma_f32_16x16x32_bf16 v[76:79], v[136:139], v[180:183], 0
	v_mfma_f32_16x16x32_bf16 v[72:75], v[144:147], v[180:183], 0
	v_mfma_f32_16x16x32_bf16 v[124:127], v[140:143], v[160:163], v[124:127]
	v_mfma_f32_16x16x32_bf16 v[120:123], v[148:151], v[160:163], v[120:123]
	v_mfma_f32_16x16x32_bf16 v[108:111], v[140:143], v[168:171], v[108:111]
	v_mfma_f32_16x16x32_bf16 v[104:107], v[148:151], v[168:171], v[104:107]
	v_mfma_f32_16x16x32_bf16 v[92:95], v[140:143], v[176:179], v[92:95]
	v_mfma_f32_16x16x32_bf16 v[88:91], v[148:151], v[176:179], v[88:91]
	v_mfma_f32_16x16x32_bf16 v[76:79], v[140:143], v[184:187], v[76:79]
	s_setprio 0
	v_mfma_f32_16x16x32_bf16 v[72:75], v[148:151], v[184:187], v[72:75]
	s_barrier
	s_add_i32 s58, 0, 0x14000
	s_add_i32 s55, s55, s36
	v_add_u32_e32 v152, s58, v134
	v_lshl_add_u64 v[204:205], s[24:25], 0, v[128:129]
	s_mov_b32 m0, s55
	ds_read_b128 v[188:191], v152
	ds_read_b128 v[192:195], v152 offset:1024
	ds_read_b128 v[196:199], v152 offset:2048
	ds_read_b128 v[200:203], v152 offset:3072
	global_load_lds_dwordx4 v[204:205], off
	s_add_i32 m0, s55, 0x2000
	v_lshl_add_u64 v[204:205], s[24:25], 0, v[130:131]
	global_load_lds_dwordx4 v[204:205], off
	s_barrier
	s_waitcnt lgkmcnt(0)
	v_mfma_f32_16x16x32_bf16 v[116:119], v[188:191], v[156:159], 0
	s_setprio 1
	v_mfma_f32_16x16x32_bf16 v[112:115], v[196:199], v[156:159], 0
	s_mov_b32 m0, s37
	v_lshl_add_u64 v[204:205], s[28:29], 0, v[128:129]
	v_mfma_f32_16x16x32_bf16 v[100:103], v[188:191], v[164:167], 0
	v_mfma_f32_16x16x32_bf16 v[96:99], v[196:199], v[164:167], 0
	v_mfma_f32_16x16x32_bf16 v[84:87], v[188:191], v[172:175], 0
	v_mfma_f32_16x16x32_bf16 v[80:83], v[196:199], v[172:175], 0
	v_mfma_f32_16x16x32_bf16 v[68:71], v[188:191], v[180:183], 0
	v_mfma_f32_16x16x32_bf16 v[64:67], v[196:199], v[180:183], 0
	v_mfma_f32_16x16x32_bf16 v[116:119], v[192:195], v[160:163], v[116:119]
	v_mfma_f32_16x16x32_bf16 v[112:115], v[200:203], v[160:163], v[112:115]
	v_mfma_f32_16x16x32_bf16 v[100:103], v[192:195], v[168:171], v[100:103]
	v_mfma_f32_16x16x32_bf16 v[96:99], v[200:203], v[168:171], v[96:99]
	v_mfma_f32_16x16x32_bf16 v[84:87], v[192:195], v[176:179], v[84:87]
	v_mfma_f32_16x16x32_bf16 v[80:83], v[200:203], v[176:179], v[80:83]
	v_mfma_f32_16x16x32_bf16 v[68:71], v[192:195], v[184:187], v[68:71]
	s_setprio 0
	v_mfma_f32_16x16x32_bf16 v[64:67], v[200:203], v[184:187], v[64:67]
	s_barrier
	ds_read_b128 v[156:159], v135 offset:16384
	ds_read_b128 v[160:163], v135 offset:17408
	ds_read_b128 v[164:167], v135 offset:18432
	ds_read_b128 v[168:171], v135 offset:19456
	ds_read_b128 v[172:175], v135 offset:20480
	ds_read_b128 v[176:179], v135 offset:21504
	ds_read_b128 v[180:183], v135 offset:22528
	ds_read_b128 v[184:187], v135 offset:23552
	global_load_lds_dwordx4 v[204:205], off
	s_mov_b32 m0, s38
	v_lshl_add_u64 v[204:205], s[28:29], 0, v[130:131]
	global_load_lds_dwordx4 v[204:205], off
	s_barrier
	s_waitcnt lgkmcnt(0)
	v_mfma_f32_16x16x32_bf16 v[60:63], v[136:139], v[156:159], 0
	s_setprio 1
	v_mfma_f32_16x16x32_bf16 v[56:59], v[144:147], v[156:159], 0
	v_mfma_f32_16x16x32_bf16 v[44:47], v[136:139], v[164:167], 0
	v_mfma_f32_16x16x32_bf16 v[40:43], v[144:147], v[164:167], 0
	v_mfma_f32_16x16x32_bf16 v[28:31], v[136:139], v[172:175], 0
	v_mfma_f32_16x16x32_bf16 v[24:27], v[144:147], v[172:175], 0
	v_mfma_f32_16x16x32_bf16 v[12:15], v[136:139], v[180:183], 0
	v_mfma_f32_16x16x32_bf16 v[8:11], v[144:147], v[180:183], 0
	v_mfma_f32_16x16x32_bf16 v[60:63], v[140:143], v[160:163], v[60:63]
	v_mfma_f32_16x16x32_bf16 v[56:59], v[148:151], v[160:163], v[56:59]
	v_mfma_f32_16x16x32_bf16 v[44:47], v[140:143], v[168:171], v[44:47]
	v_mfma_f32_16x16x32_bf16 v[40:43], v[148:151], v[168:171], v[40:43]
	v_mfma_f32_16x16x32_bf16 v[28:31], v[140:143], v[176:179], v[28:31]
	v_mfma_f32_16x16x32_bf16 v[24:27], v[148:151], v[176:179], v[24:27]
	v_mfma_f32_16x16x32_bf16 v[12:15], v[140:143], v[184:187], v[12:15]
	s_setprio 0
	v_mfma_f32_16x16x32_bf16 v[8:11], v[148:151], v[184:187], v[8:11]
	s_barrier
; #define PG8_STAGE(bufoff, gbase, voff) do { _Pragma("unroll") for (int _i = 0; _i < 2; ++_i) \
;         __builtin_amdgcn_global_load_lds((const unsigned*)((const char*)(gbase) + (voff)[_i]), (LAS unsigned*)(lds + (bufoff) + ldsw + _i * 8192), 16, 0, 0); } while (0)
; #define PG8_LDA(dst, b, h) do { _Pragma("unroll") for (int m = 0; m < 4; ++m) _Pragma("unroll") for (int k = 0; k < 2; ++k) dst[m][k] = *(const LAS bf16x8*)(lds + PG8_SA(b, h) + aoff + m * 2048 + k * 1024); } while (0)
; #define PG8_LDB(dst, b, h) do { _Pragma("unroll") for (int n = 0; n < 2; ++n) _Pragma("unroll") for (int k = 0; k < 2; ++k) dst[n][k] = *(const LAS bf16x8*)(lds + PG8_SB(b, h) + boff + n * 2048 + k * 1024); } while (0)
; #define PG8_MMA(ai, bj, At, Bt) do { __builtin_amdgcn_s_setprio(1); _Pragma("unroll") for (int m = 0; m < 4; ++m) _Pragma("unroll") for (int n = 0; n < 2; ++n) _Pragma("unroll") for (int k = 0; k < 2; ++k) \
;         acc[ai][bj][m][n] = __builtin_amdgcn_mfma_f32_16x16x32_bf16(Bt[n][k], At[m][k], acc[ai][bj][m][n], 0, 0, 0); __builtin_amdgcn_s_setprio(0); } while (0)
; #define PG8_WAIT_V(n) asm volatile("s_waitcnt vmcnt(" #n ")" ::: "memory")
; #define PG8_WAIT_L(n) asm volatile("s_waitcnt lgkmcnt(" #n ")" ::: "memory")
; #define PG8_BAR __builtin_amdgcn_s_barrier()
; #define PG8_SCHED __builtin_amdgcn_sched_barrier(0)
; template <class Epi>
; __device__ __forceinline__ void gemm_phase(LAS unsigned char* lds, const Gemm g, const StaticOrder& S, const Epi& E) {
;     ...
;             PG8_STAGE(PG8_SB(0, 1), b2 + hstepB, voffB);
;             PG8_WAIT_V(6); PG8_BAR; PG8_MMA(1, 1, At, B1); PG8_BAR;
;             PG8_LDB(B0, 1, 0); PG8_SCHED; PG8_LDA(At, 1, 0); PG8_STAGE(PG8_SA(0, 1), a2 + hstepA, voffA);
;             PG8_WAIT_L(8); PG8_BAR; PG8_WAIT_L(0); PG8_MMA(0, 0, At, B0); PG8_BAR; PG8_SCHED;
;             PG8_LDB(B1, 1, 1); PG8_STAGE(PG8_SB(1, 0), b3, voffB);
	s_add_u32 s56, s24, 0x80000
	s_addc_u32 s57, s25, 0
	s_add_i32 s55, s58, s36
	s_mov_b32 m0, s55
	v_lshl_add_u64 v[136:137], s[56:57], 0, v[128:129]
	global_load_lds_dwordx4 v[136:137], off
	s_add_i32 m0, s55, 0x2000
	v_lshl_add_u64 v[136:137], s[56:57], 0, v[130:131]
	global_load_lds_dwordx4 v[136:137], off
	s_waitcnt vmcnt(6)
	s_barrier
	v_mfma_f32_16x16x32_bf16 v[52:55], v[188:191], v[156:159], 0
	s_setprio 1
	v_mfma_f32_16x16x32_bf16 v[48:51], v[196:199], v[156:159], 0
	s_add_i32 s55, 0, 0x18000
	v_add_u32_e32 v148, s55, v134
	v_mfma_f32_16x16x32_bf16 v[36:39], v[188:191], v[164:167], 0
	v_mfma_f32_16x16x32_bf16 v[32:35], v[196:199], v[164:167], 0
	v_mfma_f32_16x16x32_bf16 v[20:23], v[188:191], v[172:175], 0
	v_mfma_f32_16x16x32_bf16 v[16:19], v[196:199], v[172:175], 0
	v_mfma_f32_16x16x32_bf16 v[4:7], v[188:191], v[180:183], 0
	v_mfma_f32_16x16x32_bf16 v[0:3], v[196:199], v[180:183], 0
	v_mfma_f32_16x16x32_bf16 v[52:55], v[192:195], v[160:163], v[52:55]
	v_mfma_f32_16x16x32_bf16 v[48:51], v[200:203], v[160:163], v[48:51]
	v_mfma_f32_16x16x32_bf16 v[36:39], v[192:195], v[168:171], v[36:39]
	v_mfma_f32_16x16x32_bf16 v[32:35], v[200:203], v[168:171], v[32:35]
	v_mfma_f32_16x16x32_bf16 v[20:23], v[192:195], v[176:179], v[20:23]
	v_mfma_f32_16x16x32_bf16 v[16:19], v[200:203], v[176:179], v[16:19]
	v_mfma_f32_16x16x32_bf16 v[4:7], v[192:195], v[184:187], v[4:7]
	s_setprio 0
	v_mfma_f32_16x16x32_bf16 v[0:3], v[200:203], v[184:187], v[0:3]
	s_barrier
	ds_read_b128 v[136:139], v148
	ds_read_b128 v[140:143], v148 offset:1024
	ds_read_b128 v[144:147], v148 offset:2048
	ds_read_b128 v[148:151], v148 offset:3072
	s_add_u32 s28, s28, 0x80000
	s_addc_u32 s29, s29, 0
	s_mov_b32 m0, s39
	v_lshl_add_u64 v[188:189], s[28:29], 0, v[128:129]
	ds_read_b128 v[156:159], v135 offset:32768
	ds_read_b128 v[160:163], v135 offset:33792
	ds_read_b128 v[164:167], v135 offset:34816
	ds_read_b128 v[168:171], v135 offset:35840
	ds_read_b128 v[172:175], v135 offset:36864
	ds_read_b128 v[176:179], v135 offset:37888
	ds_read_b128 v[180:183], v135 offset:38912
	ds_read_b128 v[184:187], v135 offset:39936
	global_load_lds_dwordx4 v[188:189], off
	s_mov_b32 m0, s40
	v_lshl_add_u64 v[188:189], s[28:29], 0, v[130:131]
	global_load_lds_dwordx4 v[188:189], off
	s_waitcnt lgkmcnt(8)
	s_barrier
	s_waitcnt lgkmcnt(0)
	v_mfma_f32_16x16x32_bf16 v[124:127], v[136:139], v[156:159], v[124:127]
	s_setprio 1
	v_mfma_f32_16x16x32_bf16 v[120:123], v[144:147], v[156:159], v[120:123]
	v_mfma_f32_16x16x32_bf16 v[108:111], v[136:139], v[164:167], v[108:111]
	v_mfma_f32_16x16x32_bf16 v[104:107], v[144:147], v[164:167], v[104:107]
	v_mfma_f32_16x16x32_bf16 v[92:95], v[136:139], v[172:175], v[92:95]
	v_mfma_f32_16x16x32_bf16 v[88:91], v[144:147], v[172:175], v[88:91]
	v_mfma_f32_16x16x32_bf16 v[76:79], v[136:139], v[180:183], v[76:79]
	v_mfma_f32_16x16x32_bf16 v[72:75], v[144:147], v[180:183], v[72:75]
	v_mfma_f32_16x16x32_bf16 v[124:127], v[140:143], v[160:163], v[124:127]
	v_mfma_f32_16x16x32_bf16 v[120:123], v[148:151], v[160:163], v[120:123]
	v_mfma_f32_16x16x32_bf16 v[108:111], v[140:143], v[168:171], v[108:111]
	v_mfma_f32_16x16x32_bf16 v[104:107], v[148:151], v[168:171], v[104:107]
	v_mfma_f32_16x16x32_bf16 v[92:95], v[140:143], v[176:179], v[92:95]
	v_mfma_f32_16x16x32_bf16 v[88:91], v[148:151], v[176:179], v[88:91]
	v_mfma_f32_16x16x32_bf16 v[76:79], v[140:143], v[184:187], v[76:79]
	s_setprio 0
	v_mfma_f32_16x16x32_bf16 v[72:75], v[148:151], v[184:187], v[72:75]
	s_barrier
	s_add_i32 s56, 0, 0x1c000
	s_add_u32 s28, s24, 0x4000
	s_addc_u32 s29, s25, 0
	s_add_i32 s55, s55, s36
	v_add_u32_e32 v152, s56, v134
	v_lshl_add_u64 v[204:205], s[28:29], 0, v[128:129]
	s_mov_b32 m0, s55
	ds_read_b128 v[188:191], v152
	ds_read_b128 v[192:195], v152 offset:1024
	ds_read_b128 v[196:199], v152 offset:2048
	ds_read_b128 v[200:203], v152 offset:3072
	global_load_lds_dwordx4 v[204:205], off
	s_add_i32 m0, s55, 0x2000
	v_lshl_add_u64 v[204:205], s[28:29], 0, v[130:131]
	global_load_lds_dwordx4 v[204:205], off
	s_barrier
; #define PG8_STAGE(bufoff, gbase, voff) do { _Pragma("unroll") for (int _i = 0; _i < 2; ++_i) \
;         __builtin_amdgcn_global_load_lds((const unsigned*)((const char*)(gbase) + (voff)[_i]), (LAS unsigned*)(lds + (bufoff) + ldsw + _i * 8192), 16, 0, 0); } while (0)
; #define PG8_LDA(dst, b, h) do { _Pragma("unroll") for (int m = 0; m < 4; ++m) _Pragma("unroll") for (int k = 0; k < 2; ++k) dst[m][k] = *(const LAS bf16x8*)(lds + PG8_SA(b, h) + aoff + m * 2048 + k * 1024); } while (0)
; #define PG8_MMA(ai, bj, At, Bt) do { __builtin_amdgcn_s_setprio(1); _Pragma("unroll") for (int m = 0; m < 4; ++m) _Pragma("unroll") for (int n = 0; n < 2; ++n) _Pragma("unroll") for (int k = 0; k < 2; ++k) \
;         acc[ai][bj][m][n] = __builtin_amdgcn_mfma_f32_16x16x32_bf16(Bt[n][k], At[m][k], acc[ai][bj][m][n], 0, 0, 0); __builtin_amdgcn_s_setprio(0); } while (0)
; #define PG8_WAIT_V(n) asm volatile("s_waitcnt vmcnt(" #n ")" ::: "memory")
; #define PG8_WAIT_L(n) asm volatile("s_waitcnt lgkmcnt(" #n ")" ::: "memory")
; #define PG8_BAR __builtin_amdgcn_s_barrier()
; #define PG8_SCHED __builtin_amdgcn_sched_barrier(0)
; template <class Epi>
; __device__ __forceinline__ void gemm_phase(LAS unsigned char* lds, const Gemm g, const StaticOrder& S, const Epi& E) {
;     ...
;             PG8_BAR; PG8_WAIT_L(0); PG8_MMA(0, 1, At, B1); PG8_BAR;
;             PG8_LDA(At, 1, 1); PG8_STAGE(PG8_SA(1, 0), a3, voffA);
;             PG8_BAR; PG8_WAIT_L(0); PG8_MMA(1, 0, At, B0); PG8_BAR; PG8_SCHED;
;             PG8_STAGE(PG8_SB(1, 1), b3 + hstepB, voffB);
;             PG8_WAIT_V(6); PG8_BAR; PG8_MMA(1, 1, At, B1); PG8_BAR;
	s_waitcnt lgkmcnt(0)
	v_mfma_f32_16x16x32_bf16 v[116:119], v[188:191], v[156:159], v[116:119]
	s_setprio 1
	v_mfma_f32_16x16x32_bf16 v[112:115], v[196:199], v[156:159], v[112:115]
	s_mov_b32 m0, s43
	v_lshl_add_u64 v[204:205], s[26:27], 0, v[128:129]
	v_mfma_f32_16x16x32_bf16 v[100:103], v[188:191], v[164:167], v[100:103]
	v_mfma_f32_16x16x32_bf16 v[96:99], v[196:199], v[164:167], v[96:99]
	v_mfma_f32_16x16x32_bf16 v[84:87], v[188:191], v[172:175], v[84:87]
	v_mfma_f32_16x16x32_bf16 v[80:83], v[196:199], v[172:175], v[80:83]
	v_mfma_f32_16x16x32_bf16 v[68:71], v[188:191], v[180:183], v[68:71]
	v_mfma_f32_16x16x32_bf16 v[64:67], v[196:199], v[180:183], v[64:67]
	v_mfma_f32_16x16x32_bf16 v[116:119], v[192:195], v[160:163], v[116:119]
	v_mfma_f32_16x16x32_bf16 v[112:115], v[200:203], v[160:163], v[112:115]
	v_mfma_f32_16x16x32_bf16 v[100:103], v[192:195], v[168:171], v[100:103]
	v_mfma_f32_16x16x32_bf16 v[96:99], v[200:203], v[168:171], v[96:99]
	v_mfma_f32_16x16x32_bf16 v[84:87], v[192:195], v[176:179], v[84:87]
	v_mfma_f32_16x16x32_bf16 v[80:83], v[200:203], v[176:179], v[80:83]
	v_mfma_f32_16x16x32_bf16 v[68:71], v[192:195], v[184:187], v[68:71]
	s_setprio 0
	v_mfma_f32_16x16x32_bf16 v[64:67], v[200:203], v[184:187], v[64:67]
	s_barrier
	ds_read_b128 v[156:159], v135 offset:49152
	ds_read_b128 v[160:163], v135 offset:50176
	ds_read_b128 v[164:167], v135 offset:51200
	ds_read_b128 v[168:171], v135 offset:52224
	ds_read_b128 v[172:175], v135 offset:53248
	ds_read_b128 v[176:179], v135 offset:54272
	ds_read_b128 v[180:183], v135 offset:55296
	ds_read_b128 v[184:187], v135 offset:56320
	global_load_lds_dwordx4 v[204:205], off
	s_mov_b32 m0, s44
	v_lshl_add_u64 v[204:205], s[26:27], 0, v[130:131]
	global_load_lds_dwordx4 v[204:205], off
	s_barrier
	s_waitcnt lgkmcnt(0)
	v_mfma_f32_16x16x32_bf16 v[60:63], v[136:139], v[156:159], v[60:63]
	s_setprio 1
	v_mfma_f32_16x16x32_bf16 v[56:59], v[144:147], v[156:159], v[56:59]
	v_mfma_f32_16x16x32_bf16 v[44:47], v[136:139], v[164:167], v[44:47]
	v_mfma_f32_16x16x32_bf16 v[40:43], v[144:147], v[164:167], v[40:43]
	v_mfma_f32_16x16x32_bf16 v[28:31], v[136:139], v[172:175], v[28:31]
	v_mfma_f32_16x16x32_bf16 v[24:27], v[144:147], v[172:175], v[24:27]
	v_mfma_f32_16x16x32_bf16 v[12:15], v[136:139], v[180:183], v[12:15]
	v_mfma_f32_16x16x32_bf16 v[8:11], v[144:147], v[180:183], v[8:11]
	v_mfma_f32_16x16x32_bf16 v[60:63], v[140:143], v[160:163], v[60:63]
	v_mfma_f32_16x16x32_bf16 v[56:59], v[148:151], v[160:163], v[56:59]
	v_mfma_f32_16x16x32_bf16 v[44:47], v[140:143], v[168:171], v[44:47]
	v_mfma_f32_16x16x32_bf16 v[40:43], v[148:151], v[168:171], v[40:43]
	v_mfma_f32_16x16x32_bf16 v[28:31], v[140:143], v[176:179], v[28:31]
	v_mfma_f32_16x16x32_bf16 v[24:27], v[148:151], v[176:179], v[24:27]
	v_mfma_f32_16x16x32_bf16 v[12:15], v[140:143], v[184:187], v[12:15]
	s_setprio 0
	v_mfma_f32_16x16x32_bf16 v[8:11], v[148:151], v[184:187], v[8:11]
	s_barrier
	s_add_u32 s24, s24, 0x84000
	s_addc_u32 s25, s25, 0
	s_add_i32 s26, s56, s36
	s_mov_b32 m0, s26
	v_lshl_add_u64 v[136:137], s[24:25], 0, v[128:129]
	global_load_lds_dwordx4 v[136:137], off
	s_add_i32 m0, s26, 0x2000
	v_lshl_add_u64 v[136:137], s[24:25], 0, v[130:131]
	global_load_lds_dwordx4 v[136:137], off
	s_waitcnt vmcnt(6)
	s_barrier
	v_mfma_f32_16x16x32_bf16 v[52:55], v[188:191], v[156:159], v[52:55]
	s_setprio 1
	v_mfma_f32_16x16x32_bf16 v[48:51], v[196:199], v[156:159], v[48:51]
	s_add_i32 s54, s54, 2
	s_add_u32 s22, s22, 0x8000
	s_addc_u32 s23, s23, 0
	s_add_u32 s51, s51, 0x8000
	s_addc_u32 s52, s52, 0
	v_mfma_f32_16x16x32_bf16 v[36:39], v[188:191], v[164:167], v[36:39]
	v_mfma_f32_16x16x32_bf16 v[32:35], v[196:199], v[164:167], v[32:35]
	v_mfma_f32_16x16x32_bf16 v[20:23], v[188:191], v[172:175], v[20:23]
	v_mfma_f32_16x16x32_bf16 v[16:19], v[196:199], v[172:175], v[16:19]
	v_mfma_f32_16x16x32_bf16 v[4:7], v[188:191], v[180:183], v[4:7]
	v_mfma_f32_16x16x32_bf16 v[0:3], v[196:199], v[180:183], v[0:3]
	v_mfma_f32_16x16x32_bf16 v[52:55], v[192:195], v[160:163], v[52:55]
	v_mfma_f32_16x16x32_bf16 v[48:51], v[200:203], v[160:163], v[48:51]
	v_mfma_f32_16x16x32_bf16 v[36:39], v[192:195], v[168:171], v[36:39]
	v_mfma_f32_16x16x32_bf16 v[32:35], v[200:203], v[168:171], v[32:35]
	v_mfma_f32_16x16x32_bf16 v[20:23], v[192:195], v[176:179], v[20:23]
	v_mfma_f32_16x16x32_bf16 v[16:19], v[200:203], v[176:179], v[16:19]
	v_mfma_f32_16x16x32_bf16 v[4:7], v[192:195], v[184:187], v[4:7]
	s_cmp_gt_u32 s54, 29
	s_setprio 0
	v_mfma_f32_16x16x32_bf16 v[0:3], v[200:203], v[184:187], v[0:3]
	s_barrier
	s_cbranch_scc0 .LBB0_141
	s_branch .Lpeel_done_141

; __device__ __forceinline__ unsigned cvt_pk_bf16(float lo, float hi) { unsigned r; asm volatile("v_cvt_pk_bf16_f32 %0, %1, %2" : "=v"(r) : "v"(lo), "v"(hi)); return r; }
;     __device__ __forceinline__ void operator()(const f32x4 (&acc)[2][2][4][2], const Unit& u, int wr, int wc, int fr, int fq) const {
;         const int row0 = u.pm * BM + wr * 64 + fr, col0 = u.pn * BM + wc * 32 + 8 * fq;
; #pragma unroll
;         for (int ai = 0; ai < 2; ++ai)
; #pragma unroll
;             for (int m = 0; m < 4; ++m) {
;                 const int rowi = row0 + ai * HALF + m * 16;
; #pragma unroll
;                 for (int bj = 0; bj < 2; ++bj) {
;                     f32x4 v0 = acc[ai][bj][m][0], v1 = acc[ai][bj][m][1];
; #pragma unroll
;                     for (int j = 0; j < 4; ++j) { const float a = fmaxf(v0[j], 0.f), b = fmaxf(v1[j], 0.f); v0[j] = a * a; v1[j] = b * b; }
;                     u32x4 w; w.x = cvt_pk_bf16(v0[0], v0[1]); w.y = cvt_pk_bf16(v0[2], v0[3]); w.z = cvt_pk_bf16(v1[0], v1[1]); w.w = cvt_pk_bf16(v1[2], v1[3]);
;                     *(u32x4*)(O + tiled_off(rowi, col0 + bj * HALF, DFF / 64)) = w;
.Lpeel_done_141:
	s_lshl_b32 s24, s20, 8
	s_lshl_b32 s5, s21, 8
	s_add_i32 s24, s24, s41
	s_or_b32 s5, s5, s42
	s_and_b32 s22, s24, 0xffffff80
	s_ashr_i32 s5, s5, 6
	s_add_i32 s20, s22, s5
	s_ashr_i32 s21, s20, 31
	v_max_f32_e32 v120, 0, v120
	s_lshl_b64 s[20:21], s[20:21], 14
	v_readlane_b32 s26, v252, 57
	v_or_b32_e32 v136, s24, v132
	v_mul_f32_e32 v140, v120, v120
	v_max_f32_e32 v121, 0, v121
	v_max_f32_e32 v122, 0, v122
	v_readlane_b32 s27, v252, 58
	s_add_u32 s20, s26, s20
	v_lshlrev_b32_e32 v137, 6, v136
	s_movk_i32 s28, 0x3c0
	v_lshlrev_b32_e32 v138, 2, v136
	v_max_f32_e32 v120, 0, v125
	v_mul_f32_e32 v125, v121, v121
	v_max_f32_e32 v121, v126, v126
	v_mul_f32_e32 v126, v122, v122
	s_addc_u32 s21, s27, s21
	s_or_b32 s15, s5, 2
	v_and_or_b32 v137, v137, s28, v133
	v_and_b32_e32 v138, 32, v138
	v_max_f32_e32 v124, 0, v124
	v_mul_f32_e32 v120, v120, v120
	v_max_f32_e32 v121, 0, v121
	v_max_f32_e32 v122, 0, v127
	v_max_f32_e32 v123, 0, v123
	s_add_i32 s22, s15, s22
	v_bitop3_b32 v139, v137, s46, v138 bitop3:0xde
	v_mul_f32_e32 v124, v124, v124
	v_mul_f32_e32 v121, v121, v121
	v_mul_f32_e32 v122, v122, v122
	v_mul_f32_e32 v123, v123, v123
	v_cvt_pk_bf16_f32 v120, v124, v120
	v_max_f32_e32 v112, 0, v112
	v_max_f32_e32 v113, 0, v113
	s_ashr_i32 s23, s22, 31
	v_cvt_pk_bf16_f32 v121, v121, v122
	v_cvt_pk_bf16_f32 v122, v140, v125
	v_cvt_pk_bf16_f32 v123, v126, v123
	global_store_dwordx4 v139, v[120:123], s[20:21]
	v_max_f32_e32 v114, 0, v114
	s_lshl_b64 s[22:23], s[22:23], 14
	v_mul_f32_e32 v120, v112, v112
	v_max_f32_e32 v112, v117, v117
	v_mul_f32_e32 v117, v113, v113
	v_max_f32_e32 v112, 0, v112
	v_max_f32_e32 v113, 0, v118
	v_mul_f32_e32 v118, v114, v114
	s_add_u32 s22, s26, s22
	v_max_f32_e32 v116, 0, v116
	v_mul_f32_e32 v112, v112, v112
	v_mul_f32_e32 v113, v113, v113
	v_max_f32_e32 v114, 0, v119
	v_max_f32_e32 v115, 0, v115
	s_addc_u32 s23, s27, s23
	s_or_b32 s25, s24, 16
	v_mul_f32_e32 v116, v116, v116
	v_mul_f32_e32 v114, v114, v114
	v_mul_f32_e32 v115, v115, v115
	v_cvt_pk_bf16_f32 v112, v116, v112
	v_cvt_pk_bf16_f32 v113, v113, v114
	s_lshr_b32 s25, s25, 3
	v_max_f32_e32 v104, 0, v104
	v_cvt_pk_bf16_f32 v114, v120, v117
	v_cvt_pk_bf16_f32 v115, v118, v115
	global_store_dwordx4 v139, v[112:115], s[22:23]
	s_and_b32 s25, s25, 10
	v_max_f32_e32 v105, 0, v105
	v_mul_f32_e32 v113, v104, v104
	v_max_f32_e32 v106, 0, v106
	s_or_b32 s25, s25, s45
	v_max_f32_e32 v104, 0, v109
	v_mul_f32_e32 v109, v105, v105
	v_max_f32_e32 v105, v110, v110
	v_mul_f32_e32 v110, v106, v106
	s_lshl_b32 s25, s25, 10
	v_max_f32_e32 v108, 0, v108
	v_mul_f32_e32 v104, v104, v104
	v_max_f32_e32 v105, 0, v105
	v_max_f32_e32 v106, 0, v111
	v_max_f32_e32 v107, 0, v107
	v_bitop3_b32 v112, v137, s25, v138 bitop3:0xde
	v_mul_f32_e32 v108, v108, v108
	v_mul_f32_e32 v105, v105, v105
	v_mul_f32_e32 v106, v106, v106
	v_mul_f32_e32 v107, v107, v107
	v_cvt_pk_bf16_f32 v104, v108, v104
	v_max_f32_e32 v96, 0, v96
	v_max_f32_e32 v97, 0, v97
	v_cvt_pk_bf16_f32 v105, v105, v106
	v_cvt_pk_bf16_f32 v106, v113, v109
	v_cvt_pk_bf16_f32 v107, v110, v107
	global_store_dwordx4 v112, v[104:107], s[20:21]
	s_nop 0
	v_max_f32_e32 v98, 0, v98
	v_mul_f32_e32 v104, v96, v96
	v_max_f32_e32 v96, v101, v101
	v_mul_f32_e32 v101, v97, v97
	v_max_f32_e32 v96, 0, v96
	v_max_f32_e32 v97, 0, v102
	v_mul_f32_e32 v102, v98, v98
	v_max_f32_e32 v100, 0, v100
	v_mul_f32_e32 v96, v96, v96
	v_mul_f32_e32 v97, v97, v97
	v_max_f32_e32 v98, 0, v103
	v_max_f32_e32 v99, 0, v99
	s_or_b32 s25, s24, 32
	v_mul_f32_e32 v100, v100, v100
	v_mul_f32_e32 v98, v98, v98
	v_mul_f32_e32 v99, v99, v99
	v_cvt_pk_bf16_f32 v96, v100, v96
	v_cvt_pk_bf16_f32 v97, v97, v98
	s_lshr_b32 s25, s25, 3
	v_max_f32_e32 v88, 0, v88
	v_cvt_pk_bf16_f32 v98, v104, v101
	v_cvt_pk_bf16_f32 v99, v102, v99
	global_store_dwordx4 v112, v[96:99], s[22:23]
	s_and_b32 s25, s25, 12
	v_max_f32_e32 v89, 0, v89
	v_mul_f32_e32 v97, v88, v88
	v_max_f32_e32 v90, 0, v90
	s_or_b32 s25, s25, s45
	v_max_f32_e32 v88, 0, v93
	v_mul_f32_e32 v93, v89, v89
	v_max_f32_e32 v89, v94, v94
	v_mul_f32_e32 v94, v90, v90
	s_lshl_b32 s25, s25, 10
	v_max_f32_e32 v92, 0, v92
	v_mul_f32_e32 v88, v88, v88
	v_max_f32_e32 v89, 0, v89
	v_max_f32_e32 v90, 0, v95
	v_max_f32_e32 v91, 0, v91
	v_bitop3_b32 v96, v137, s25, v138 bitop3:0xde
	v_mul_f32_e32 v92, v92, v92
	v_mul_f32_e32 v89, v89, v89
	v_mul_f32_e32 v90, v90, v90
	v_mul_f32_e32 v91, v91, v91
	v_cvt_pk_bf16_f32 v88, v92, v88
	v_max_f32_e32 v80, 0, v80
	v_max_f32_e32 v81, 0, v81
	v_cvt_pk_bf16_f32 v89, v89, v90
	v_cvt_pk_bf16_f32 v90, v97, v93
	v_cvt_pk_bf16_f32 v91, v94, v91
	global_store_dwordx4 v96, v[88:91], s[20:21]
	s_nop 0
	v_max_f32_e32 v82, 0, v82
	v_mul_f32_e32 v88, v80, v80
	v_max_f32_e32 v80, v85, v85
	v_mul_f32_e32 v85, v81, v81
	v_max_f32_e32 v80, 0, v80
	v_max_f32_e32 v81, 0, v86
	v_mul_f32_e32 v86, v82, v82
	v_max_f32_e32 v84, 0, v84
	v_mul_f32_e32 v80, v80, v80
	v_mul_f32_e32 v81, v81, v81
	v_max_f32_e32 v82, 0, v87
	v_max_f32_e32 v83, 0, v83
	s_or_b32 s24, s24, 48
	v_mul_f32_e32 v84, v84, v84
	v_mul_f32_e32 v82, v82, v82
	v_mul_f32_e32 v83, v83, v83
	v_cvt_pk_bf16_f32 v80, v84, v80
	v_cvt_pk_bf16_f32 v81, v81, v82
	s_lshr_b32 s24, s24, 3
	v_max_f32_e32 v72, 0, v72
	v_cvt_pk_bf16_f32 v82, v88, v85
	v_cvt_pk_bf16_f32 v83, v86, v83
	global_store_dwordx4 v96, v[80:83], s[22:23]
	s_and_b32 s24, s24, 14
	v_max_f32_e32 v73, 0, v73
	v_mul_f32_e32 v81, v72, v72
	v_max_f32_e32 v74, 0, v74
	s_or_b32 s24, s24, s45
	v_max_f32_e32 v72, 0, v77
	v_mul_f32_e32 v77, v73, v73
	v_max_f32_e32 v73, v78, v78
	v_mul_f32_e32 v78, v74, v74
	s_lshl_b32 s24, s24, 10
	v_max_f32_e32 v76, 0, v76
	v_mul_f32_e32 v72, v72, v72
	v_max_f32_e32 v73, 0, v73
; __device__ __forceinline__ unsigned cvt_pk_bf16(float lo, float hi) { unsigned r; asm volatile("v_cvt_pk_bf16_f32 %0, %1, %2" : "=v"(r) : "v"(lo), "v"(hi)); return r; }
;     __device__ __forceinline__ void operator()(const f32x4 (&acc)[2][2][4][2], const Unit& u, int wr, int wc, int fr, int fq) const {
;         const int row0 = u.pm * BM + wr * 64 + fr, col0 = u.pn * BM + wc * 32 + 8 * fq;
; #pragma unroll
;         for (int ai = 0; ai < 2; ++ai)
; #pragma unroll
;             for (int m = 0; m < 4; ++m) {
;                 const int rowi = row0 + ai * HALF + m * 16;
; #pragma unroll
;                 for (int bj = 0; bj < 2; ++bj) {
;                     f32x4 v0 = acc[ai][bj][m][0], v1 = acc[ai][bj][m][1];
; #pragma unroll
;                     for (int j = 0; j < 4; ++j) { const float a = fmaxf(v0[j], 0.f), b = fmaxf(v1[j], 0.f); v0[j] = a * a; v1[j] = b * b; }
;                     u32x4 w; w.x = cvt_pk_bf16(v0[0], v0[1]); w.y = cvt_pk_bf16(v0[2], v0[3]); w.z = cvt_pk_bf16(v1[0], v1[1]); w.w = cvt_pk_bf16(v1[2], v1[3]);
;                     *(u32x4*)(O + tiled_off(rowi, col0 + bj * HALF, DFF / 64)) = w;
	v_max_f32_e32 v74, 0, v79
	v_max_f32_e32 v75, 0, v75
	v_bitop3_b32 v80, v137, s24, v138 bitop3:0xde
	v_mul_f32_e32 v76, v76, v76
	v_mul_f32_e32 v73, v73, v73
	v_mul_f32_e32 v74, v74, v74
	v_mul_f32_e32 v75, v75, v75
	v_cvt_pk_bf16_f32 v72, v76, v72
	v_max_f32_e32 v64, 0, v64
	v_cvt_pk_bf16_f32 v73, v73, v74
	v_cvt_pk_bf16_f32 v74, v81, v77
	v_cvt_pk_bf16_f32 v75, v78, v75
	global_store_dwordx4 v80, v[72:75], s[20:21]
	v_max_f32_e32 v65, 0, v65
	v_max_f32_e32 v66, 0, v66
	v_mul_f32_e32 v72, v64, v64
	v_max_f32_e32 v64, 0, v69
	v_mul_f32_e32 v69, v65, v65
	v_max_f32_e32 v65, v70, v70
	v_mul_f32_e32 v70, v66, v66
	v_max_f32_e32 v68, 0, v68
	v_mul_f32_e32 v64, v64, v64
	v_max_f32_e32 v65, 0, v65
	v_max_f32_e32 v66, 0, v71
	v_max_f32_e32 v67, 0, v67
	v_mul_f32_e32 v68, v68, v68
	v_mul_f32_e32 v65, v65, v65
	v_mul_f32_e32 v66, v66, v66
	v_mul_f32_e32 v67, v67, v67
	v_cvt_pk_bf16_f32 v64, v68, v64
	v_cvt_pk_bf16_f32 v65, v65, v66
	v_cvt_pk_bf16_f32 v66, v72, v69
	v_cvt_pk_bf16_f32 v67, v70, v67
	global_store_dwordx4 v80, v[64:67], s[22:23]
	s_nop 0
	v_max_f32_e32 v56, 0, v56
	v_add_u32_e32 v64, 0x80, v136
	v_and_b32_e32 v65, 0xffffff80, v64
	v_lshlrev_b32_e32 v66, 6, v64
	v_lshlrev_b32_e32 v64, 2, v64
	v_and_or_b32 v66, v66, s28, v133
	v_and_b32_e32 v64, 32, v64
	v_bitop3_b32 v152, v66, s46, v64 bitop3:0xde
	v_mul_f32_e32 v64, v56, v56
	v_max_f32_e32 v57, 0, v57
	v_max_f32_e32 v58, 0, v58
	v_max_f32_e32 v60, 0, v60
	v_max_f32_e32 v56, 0, v61
	v_mul_f32_e32 v61, v57, v57
	v_max_f32_e32 v57, v62, v62
	v_mul_f32_e32 v62, v58, v58
	v_mul_f32_e32 v60, v60, v60
	v_mul_f32_e32 v56, v56, v56
	v_max_f32_e32 v57, 0, v57
	v_max_f32_e32 v58, 0, v63
	v_mul_f32_e32 v57, v57, v57
	v_mul_f32_e32 v58, v58, v58
	v_cvt_pk_bf16_f32 v56, v60, v56
	v_add_u32_e32 v60, s5, v65
	v_cvt_pk_bf16_f32 v57, v57, v58
	v_cvt_pk_bf16_f32 v58, v64, v61
	v_ashrrev_i32_e32 v61, 31, v60
	v_max_f32_e32 v59, 0, v59
	v_lshlrev_b64 v[60:61], 14, v[60:61]
	v_mul_f32_e32 v59, v59, v59
	v_lshl_add_u64 v[60:61], s[26:27], 0, v[60:61]
	v_cvt_pk_bf16_f32 v59, v62, v59
	v_lshl_add_u64 v[62:63], v[60:61], 0, v[152:153]
	v_max_f32_e32 v48, 0, v48
	global_store_dwordx4 v[62:63], v[56:59], off
	s_nop 0
	v_max_f32_e32 v49, 0, v49
	v_mul_f32_e32 v56, v48, v48
	v_max_f32_e32 v50, 0, v50
	v_max_f32_e32 v52, 0, v52
	v_max_f32_e32 v48, 0, v53
	v_mul_f32_e32 v53, v49, v49
	v_max_f32_e32 v49, v54, v54
	v_mul_f32_e32 v54, v50, v50
	v_mul_f32_e32 v52, v52, v52
	v_mul_f32_e32 v48, v48, v48
	v_max_f32_e32 v49, 0, v49
	v_max_f32_e32 v50, 0, v55
	v_mul_f32_e32 v49, v49, v49
	v_mul_f32_e32 v50, v50, v50
	v_cvt_pk_bf16_f32 v48, v52, v48
	v_add_u32_e32 v52, s15, v65
	v_cvt_pk_bf16_f32 v49, v49, v50
	v_cvt_pk_bf16_f32 v50, v56, v53
	v_ashrrev_i32_e32 v53, 31, v52
	v_max_f32_e32 v51, 0, v51
	v_lshlrev_b64 v[52:53], 14, v[52:53]
	v_mul_f32_e32 v51, v51, v51
	v_lshl_add_u64 v[52:53], s[26:27], 0, v[52:53]
	v_cvt_pk_bf16_f32 v51, v54, v51
	v_lshl_add_u64 v[54:55], v[52:53], 0, v[152:153]
	global_store_dwordx4 v[54:55], v[48:51], off
	s_nop 1
	v_add_u32_e32 v48, 0x90, v136
	v_lshrrev_b32_e32 v49, 3, v48
	v_and_or_b32 v49, v49, 10, s45
	v_lshlrev_b32_e32 v50, 6, v48
	v_lshlrev_b32_e32 v48, 2, v48
	v_and_or_b32 v50, v50, s28, v133
	v_lshlrev_b32_e32 v49, 10, v49
	v_and_b32_e32 v48, 32, v48
	v_max_f32_e32 v40, 0, v40
	v_max_f32_e32 v41, 0, v41
	v_max_f32_e32 v42, 0, v42
	v_bitop3_b32 v152, v50, v49, v48 bitop3:0xde
	v_mul_f32_e32 v48, v40, v40
	v_max_f32_e32 v40, v45, v45
	v_mul_f32_e32 v45, v41, v41
	v_max_f32_e32 v41, v46, v46
	v_mul_f32_e32 v46, v42, v42
	v_max_f32_e32 v44, 0, v44
	v_max_f32_e32 v40, 0, v40
	v_max_f32_e32 v41, 0, v41
	v_max_f32_e32 v42, 0, v47
	v_mul_f32_e32 v44, v44, v44
	v_mul_f32_e32 v40, v40, v40
	v_mul_f32_e32 v41, v41, v41
	v_max_f32_e32 v43, 0, v43
	v_mul_f32_e32 v42, v42, v42
	v_mul_f32_e32 v43, v43, v43
	v_cvt_pk_bf16_f32 v40, v44, v40
	v_cvt_pk_bf16_f32 v41, v41, v42
	v_cvt_pk_bf16_f32 v42, v48, v45
	v_lshl_add_u64 v[44:45], v[60:61], 0, v[152:153]
	v_max_f32_e32 v32, 0, v32
	v_max_f32_e32 v33, 0, v33
	v_max_f32_e32 v34, 0, v34
	v_cvt_pk_bf16_f32 v43, v46, v43
	global_store_dwordx4 v[44:45], v[40:43], off
	s_nop 0
	v_max_f32_e32 v36, 0, v36
	v_mul_f32_e32 v40, v32, v32
	v_max_f32_e32 v32, v37, v37
	v_mul_f32_e32 v37, v33, v33
	v_max_f32_e32 v33, v38, v38
; __device__ __forceinline__ unsigned cvt_pk_bf16(float lo, float hi) { unsigned r; asm volatile("v_cvt_pk_bf16_f32 %0, %1, %2" : "=v"(r) : "v"(lo), "v"(hi)); return r; }
; #define PG8_WAIT_V(n) asm volatile("s_waitcnt vmcnt(" #n ")" ::: "memory")
; #define PG8_BAR __builtin_amdgcn_s_barrier()
; template <class Epi>
; __device__ __forceinline__ void gemm_phase(LAS unsigned char* lds, const Gemm g, const StaticOrder& S, const Epi& E) {
;     ...
;         E(acc, cur, wr, wc, fr, fq);
;         if (!has_next) break;
; #pragma unroll
;         for (int a = 0; a < 2; ++a)
; #pragma unroll
;             for (int b = 0; b < 2; ++b)
; #pragma unroll
;                 for (int m = 0; m < 4; ++m)
; #pragma unroll
;                     for (int n = 0; n < 2; ++n) acc[a][b][m][n] = (f32x4){0.f, 0.f, 0.f, 0.f};
;         cur = nxt; cA = nA; cB = nB; ++ui;
;     }
;     PG8_WAIT_V(0);
;     if (wr == 0) PG8_BAR;
;     PG8_BAR;
;     __device__ __forceinline__ void operator()(const f32x4 (&acc)[2][2][4][2], const Unit& u, int wr, int wc, int fr, int fq) const {
;     ...
;             for (int m = 0; m < 4; ++m) {
;                 const int rowi = row0 + ai * HALF + m * 16;
; #pragma unroll
;                 for (int bj = 0; bj < 2; ++bj) {
;                     f32x4 v0 = acc[ai][bj][m][0], v1 = acc[ai][bj][m][1];
; #pragma unroll
;                     for (int j = 0; j < 4; ++j) { const float a = fmaxf(v0[j], 0.f), b = fmaxf(v1[j], 0.f); v0[j] = a * a; v1[j] = b * b; }
;                     u32x4 w; w.x = cvt_pk_bf16(v0[0], v0[1]); w.y = cvt_pk_bf16(v0[2], v0[3]); w.z = cvt_pk_bf16(v1[0], v1[1]); w.w = cvt_pk_bf16(v1[2], v1[3]);
;                     *(u32x4*)(O + tiled_off(rowi, col0 + bj * HALF, DFF / 64)) = w;
	v_mul_f32_e32 v38, v34, v34
	v_max_f32_e32 v32, 0, v32
	v_max_f32_e32 v33, 0, v33
	v_max_f32_e32 v34, 0, v39
	v_mul_f32_e32 v36, v36, v36
	v_mul_f32_e32 v32, v32, v32
	v_mul_f32_e32 v33, v33, v33
	v_max_f32_e32 v35, 0, v35
	v_mul_f32_e32 v34, v34, v34
	v_mul_f32_e32 v35, v35, v35
	v_cvt_pk_bf16_f32 v32, v36, v32
	v_cvt_pk_bf16_f32 v33, v33, v34
	v_cvt_pk_bf16_f32 v34, v40, v37
	v_lshl_add_u64 v[36:37], v[52:53], 0, v[152:153]
	v_cvt_pk_bf16_f32 v35, v38, v35
	global_store_dwordx4 v[36:37], v[32:35], off
	s_nop 1
	v_add_u32_e32 v32, 0xa0, v136
	v_lshrrev_b32_e32 v33, 3, v32
	v_and_or_b32 v33, v33, 12, s45
	v_lshlrev_b32_e32 v34, 6, v32
	v_lshlrev_b32_e32 v32, 2, v32
	v_and_or_b32 v34, v34, s28, v133
	v_lshlrev_b32_e32 v33, 10, v33
	v_and_b32_e32 v32, 32, v32
	v_max_f32_e32 v24, 0, v24
	v_max_f32_e32 v25, 0, v25
	v_max_f32_e32 v26, 0, v26
	v_bitop3_b32 v152, v34, v33, v32 bitop3:0xde
	v_mul_f32_e32 v32, v24, v24
	v_max_f32_e32 v24, v29, v29
	v_mul_f32_e32 v29, v25, v25
	v_max_f32_e32 v25, v30, v30
	v_mul_f32_e32 v30, v26, v26
	v_max_f32_e32 v28, 0, v28
	v_max_f32_e32 v24, 0, v24
	v_max_f32_e32 v25, 0, v25
	v_max_f32_e32 v26, 0, v31
	v_mul_f32_e32 v28, v28, v28
	v_mul_f32_e32 v24, v24, v24
	v_mul_f32_e32 v25, v25, v25
	v_max_f32_e32 v27, 0, v27
	v_mul_f32_e32 v26, v26, v26
	v_mul_f32_e32 v27, v27, v27
	v_cvt_pk_bf16_f32 v24, v28, v24
	v_cvt_pk_bf16_f32 v25, v25, v26
	v_cvt_pk_bf16_f32 v26, v32, v29
	v_lshl_add_u64 v[28:29], v[60:61], 0, v[152:153]
	v_max_f32_e32 v16, 0, v16
	v_max_f32_e32 v17, 0, v17
	v_max_f32_e32 v18, 0, v18
	v_cvt_pk_bf16_f32 v27, v30, v27
	global_store_dwordx4 v[28:29], v[24:27], off
	s_nop 0
	v_max_f32_e32 v20, 0, v20
	v_mul_f32_e32 v24, v16, v16
	v_max_f32_e32 v16, v21, v21
	v_mul_f32_e32 v21, v17, v17
	v_max_f32_e32 v17, v22, v22
	v_mul_f32_e32 v22, v18, v18
	v_max_f32_e32 v16, 0, v16
	v_max_f32_e32 v17, 0, v17
	v_max_f32_e32 v18, 0, v23
	v_mul_f32_e32 v20, v20, v20
	v_mul_f32_e32 v16, v16, v16
	v_mul_f32_e32 v17, v17, v17
	v_max_f32_e32 v19, 0, v19
	v_mul_f32_e32 v18, v18, v18
	v_mul_f32_e32 v19, v19, v19
	v_cvt_pk_bf16_f32 v16, v20, v16
	v_cvt_pk_bf16_f32 v17, v17, v18
	v_cvt_pk_bf16_f32 v18, v24, v21
	v_lshl_add_u64 v[20:21], v[52:53], 0, v[152:153]
	v_cvt_pk_bf16_f32 v19, v22, v19
	global_store_dwordx4 v[20:21], v[16:19], off
	s_nop 1
	v_add_u32_e32 v16, 0xb0, v136
	v_lshrrev_b32_e32 v17, 3, v16
	v_and_or_b32 v17, v17, 14, s45
	v_lshlrev_b32_e32 v18, 6, v16
	v_lshlrev_b32_e32 v16, 2, v16
	v_and_or_b32 v18, v18, s28, v133
	v_lshlrev_b32_e32 v17, 10, v17
	v_and_b32_e32 v16, 32, v16
	v_max_f32_e32 v8, 0, v8
	v_max_f32_e32 v9, 0, v9
	v_max_f32_e32 v10, 0, v10
	v_bitop3_b32 v152, v18, v17, v16 bitop3:0xde
	v_mul_f32_e32 v16, v8, v8
	v_max_f32_e32 v8, v13, v13
	v_mul_f32_e32 v13, v9, v9
	v_max_f32_e32 v9, v14, v14
	v_mul_f32_e32 v14, v10, v10
	v_max_f32_e32 v12, 0, v12
	v_max_f32_e32 v8, 0, v8
	v_max_f32_e32 v9, 0, v9
	v_max_f32_e32 v10, 0, v15
	v_mul_f32_e32 v12, v12, v12
	v_mul_f32_e32 v8, v8, v8
	v_mul_f32_e32 v9, v9, v9
	v_max_f32_e32 v11, 0, v11
	v_mul_f32_e32 v10, v10, v10
	v_mul_f32_e32 v11, v11, v11
	v_cvt_pk_bf16_f32 v8, v12, v8
	v_cvt_pk_bf16_f32 v9, v9, v10
	v_cvt_pk_bf16_f32 v10, v16, v13
	v_lshl_add_u64 v[12:13], v[60:61], 0, v[152:153]
	v_max_f32_e32 v0, 0, v0
	v_max_f32_e32 v1, 0, v1
	v_max_f32_e32 v2, 0, v2
	v_cvt_pk_bf16_f32 v11, v14, v11
	global_store_dwordx4 v[12:13], v[8:11], off
	s_nop 0
	v_max_f32_e32 v4, 0, v4
	v_mul_f32_e32 v8, v0, v0
	v_max_f32_e32 v0, v5, v5
	v_mul_f32_e32 v5, v1, v1
	v_max_f32_e32 v1, v6, v6
	v_mul_f32_e32 v6, v2, v2
	v_max_f32_e32 v0, 0, v0
	v_max_f32_e32 v1, 0, v1
	v_max_f32_e32 v2, 0, v7
	v_mul_f32_e32 v4, v4, v4
	v_mul_f32_e32 v0, v0, v0
	v_mul_f32_e32 v1, v1, v1
	v_max_f32_e32 v3, 0, v3
	v_mul_f32_e32 v2, v2, v2
	s_mov_b32 s54, 0xd00ab22c
	v_mul_f32_e32 v3, v3, v3
	v_cvt_pk_bf16_f32 v0, v4, v0
	v_cvt_pk_bf16_f32 v1, v1, v2
	v_cvt_pk_bf16_f32 v2, v8, v5
	v_lshl_add_u64 v[4:5], v[52:53], 0, v[152:153]
	s_and_b64 vcc, exec, s[0:1]
	s_mov_b32 s21, s4
	s_mov_b32 s20, s14
	s_mov_b64 s[24:25], s[18:19]
	s_mov_b64 s[22:23], s[16:17]
	s_mov_b32 s55, 0x3febb5fa
	v_cvt_pk_bf16_f32 v3, v6, v3
	global_store_dwordx4 v[4:5], v[0:3], off
	s_cbranch_vccz .LBB0_134
	s_waitcnt vmcnt(0)
	s_cmpk_gt_u32 s31, 0xff
	s_cbranch_scc1 .LBB0_145
	s_barrier

; #define PG8_STAGE(bufoff, gbase, voff) do { _Pragma("unroll") for (int _i = 0; _i < 2; ++_i) \
;         __builtin_amdgcn_global_load_lds((const unsigned*)((const char*)(gbase) + (voff)[_i]), (LAS unsigned*)(lds + (bufoff) + ldsw + _i * 8192), 16, 0, 0); } while (0)
; #define PG8_LDA(dst, b, h) do { _Pragma("unroll") for (int m = 0; m < 4; ++m) _Pragma("unroll") for (int k = 0; k < 2; ++k) dst[m][k] = *(const LAS bf16x8*)(lds + PG8_SA(b, h) + aoff + m * 2048 + k * 1024); } while (0)
; #define PG8_LDB(dst, b, h) do { _Pragma("unroll") for (int n = 0; n < 2; ++n) _Pragma("unroll") for (int k = 0; k < 2; ++k) dst[n][k] = *(const LAS bf16x8*)(lds + PG8_SB(b, h) + boff + n * 2048 + k * 1024); } while (0)
; #define PG8_BAR __builtin_amdgcn_s_barrier()
; template <class Epi>
; __device__ __forceinline__ void gemm_phase(LAS unsigned char* lds, const Gemm g, const StaticOrder& S, const Epi& E) {
;     ...
;         for (int t = 0; t < nt; t += 2) {
;             const bool last = (t == nt - 2);
;             const char* a1 = cA + (size_t)(t + 1) * kstep;
;             const char* a2 = last ? nA : cA + (size_t)(t + 2) * kstep; const char* b2 = last ? nB : cB + (size_t)(t + 2) * kstep;
;             const char* a3 = a2 + kstep; const char* b3 = b2 + kstep;
;             PG8_LDB(B0, 0, 0); PG8_SCHED; PG8_LDA(At, 0, 0); PG8_STAGE(PG8_SA(1, 1), a1 + hstepA, voffA);
;             PG8_WAIT_L(8); PG8_BAR; PG8_WAIT_L(0); PG8_MMA(0, 0, At, B0); PG8_BAR; PG8_SCHED;
;             PG8_LDB(B1, 0, 1); PG8_STAGE(PG8_SB(0, 0), b2, voffB);
;             PG8_BAR; PG8_WAIT_L(0); PG8_MMA(0, 1, At, B1); PG8_BAR;
;             PG8_LDA(At, 0, 1); PG8_STAGE(PG8_SA(0, 0), a2, voffA);
;             PG8_BAR; PG8_WAIT_L(0); PG8_MMA(1, 0, At, B0); PG8_BAR; PG8_SCHED;
;             PG8_STAGE(PG8_SB(0, 1), b2 + hstepB, voffB);
;             PG8_WAIT_V(6); PG8_BAR; PG8_MMA(1, 1, At, B1); PG8_BAR;
;             PG8_LDB(B0, 1, 0); PG8_SCHED; PG8_LDA(At, 1, 0); PG8_STAGE(PG8_SA(0, 1), a2 + hstepA, voffA);
;             PG8_WAIT_L(8); PG8_BAR; PG8_WAIT_L(0); PG8_MMA(0, 0, At, B0); PG8_BAR; PG8_SCHED;
;     ...
; #pragma unroll
;         for (int a = 0; a < 2; ++a)
; #pragma unroll
;             for (int b = 0; b < 2; ++b)
; #pragma unroll
;                 for (int m = 0; m < 4; ++m)
; #pragma unroll
;                     for (int n = 0; n < 2; ++n) acc[a][b][m][n] = (f32x4){0.f, 0.f, 0.f, 0.f};
.LBB0_186:
	s_add_u32 s4, s24, 0x4000
	s_addc_u32 s5, s25, 0
	s_add_u32 s50, s22, 0x8000
	s_addc_u32 s51, s23, 0
	s_mov_b32 s22, 0
	s_add_i32 s54, s22, 2
	s_add_u32 s23, s4, 0x4000
	s_addc_u32 s24, s5, 0
	s_cmp_eq_u32 s40, s22
	s_cselect_b32 s26, s6, s23
	s_cselect_b32 s27, s7, s24
	s_cselect_b32 s24, s20, s50
	s_cselect_b32 s25, s21, s51
	s_add_u32 s22, s26, 0x4000
	s_addc_u32 s23, s27, 0
	s_add_i32 s55, 0, 0x10000
	v_add_u32_e32 v140, s55, v207
	ds_read_b128 v[128:131], v140
	ds_read_b128 v[132:135], v140 offset:1024
	ds_read_b128 v[136:139], v140 offset:2048
	ds_read_b128 v[140:143], v140 offset:3072
	v_lshl_add_u64 v[186:187], s[4:5], 0, v[158:159]
	s_add_i32 m0, s33, 0xc000
	ds_read_b128 v[144:147], v209
	ds_read_b128 v[148:151], v209 offset:1024
	ds_read_b128 v[162:165], v209 offset:2048
	ds_read_b128 v[166:169], v209 offset:3072
	ds_read_b128 v[170:173], v209 offset:4096
	ds_read_b128 v[174:177], v209 offset:5120
	ds_read_b128 v[178:181], v209 offset:6144
	ds_read_b128 v[182:185], v209 offset:7168
	global_load_lds_dwordx4 v[186:187], off
	s_add_i32 m0, s33, 0xe000
	v_lshl_add_u64 v[186:187], s[4:5], 0, v[160:161]
	global_load_lds_dwordx4 v[186:187], off
	s_waitcnt lgkmcnt(8)
	s_barrier
	s_waitcnt lgkmcnt(0)
	v_mfma_f32_16x16x32_bf16 v[124:127], v[128:131], v[144:147], 0
	s_setprio 1
	v_mfma_f32_16x16x32_bf16 v[120:123], v[136:139], v[144:147], 0
	v_mfma_f32_16x16x32_bf16 v[116:119], v[128:131], v[162:165], 0
	v_mfma_f32_16x16x32_bf16 v[112:115], v[136:139], v[162:165], 0
	v_mfma_f32_16x16x32_bf16 v[108:111], v[128:131], v[170:173], 0
	v_mfma_f32_16x16x32_bf16 v[104:107], v[136:139], v[170:173], 0
	v_mfma_f32_16x16x32_bf16 v[100:103], v[128:131], v[178:181], 0
	v_mfma_f32_16x16x32_bf16 v[96:99], v[136:139], v[178:181], 0
	v_mfma_f32_16x16x32_bf16 v[124:127], v[132:135], v[148:151], v[124:127]
	v_mfma_f32_16x16x32_bf16 v[120:123], v[140:143], v[148:151], v[120:123]
	v_mfma_f32_16x16x32_bf16 v[116:119], v[132:135], v[166:169], v[116:119]
	v_mfma_f32_16x16x32_bf16 v[112:115], v[140:143], v[166:169], v[112:115]
	v_mfma_f32_16x16x32_bf16 v[108:111], v[132:135], v[174:177], v[108:111]
	v_mfma_f32_16x16x32_bf16 v[104:107], v[140:143], v[174:177], v[104:107]
	v_mfma_f32_16x16x32_bf16 v[100:103], v[132:135], v[182:185], v[100:103]
	s_setprio 0
	v_mfma_f32_16x16x32_bf16 v[96:99], v[140:143], v[182:185], v[96:99]
	s_barrier
	s_add_i32 s58, 0, 0x14000
	s_add_i32 s55, s55, s31
	v_add_u32_e32 v198, s58, v207
	v_lshl_add_u64 v[202:203], s[24:25], 0, v[152:153]
	s_mov_b32 m0, s55
	ds_read_b128 v[186:189], v198
	ds_read_b128 v[190:193], v198 offset:1024
	ds_read_b128 v[194:197], v198 offset:2048
	ds_read_b128 v[198:201], v198 offset:3072
	global_load_lds_dwordx4 v[202:203], off
	s_add_i32 m0, s55, 0x2000
	v_lshl_add_u64 v[202:203], s[24:25], 0, v[156:157]
	global_load_lds_dwordx4 v[202:203], off
	s_barrier
	s_waitcnt lgkmcnt(0)
	v_mfma_f32_16x16x32_bf16 v[92:95], v[186:189], v[144:147], 0
	s_setprio 1
	v_mfma_f32_16x16x32_bf16 v[88:91], v[194:197], v[144:147], 0
	s_mov_b32 m0, s33
	v_lshl_add_u64 v[202:203], s[26:27], 0, v[152:153]
	v_mfma_f32_16x16x32_bf16 v[84:87], v[186:189], v[162:165], 0
	v_mfma_f32_16x16x32_bf16 v[80:83], v[194:197], v[162:165], 0
	v_mfma_f32_16x16x32_bf16 v[76:79], v[186:189], v[170:173], 0
	v_mfma_f32_16x16x32_bf16 v[72:75], v[194:197], v[170:173], 0
	v_mfma_f32_16x16x32_bf16 v[68:71], v[186:189], v[178:181], 0
	v_mfma_f32_16x16x32_bf16 v[64:67], v[194:197], v[178:181], 0
	v_mfma_f32_16x16x32_bf16 v[92:95], v[190:193], v[148:151], v[92:95]
	v_mfma_f32_16x16x32_bf16 v[88:91], v[198:201], v[148:151], v[88:91]
	v_mfma_f32_16x16x32_bf16 v[84:87], v[190:193], v[166:169], v[84:87]
	v_mfma_f32_16x16x32_bf16 v[80:83], v[198:201], v[166:169], v[80:83]
	v_mfma_f32_16x16x32_bf16 v[76:79], v[190:193], v[174:177], v[76:79]
	v_mfma_f32_16x16x32_bf16 v[72:75], v[198:201], v[174:177], v[72:75]
	v_mfma_f32_16x16x32_bf16 v[68:71], v[190:193], v[182:185], v[68:71]
	s_setprio 0
	v_mfma_f32_16x16x32_bf16 v[64:67], v[198:201], v[182:185], v[64:67]
	s_barrier
	ds_read_b128 v[144:147], v209 offset:16384
	ds_read_b128 v[148:151], v209 offset:17408
	ds_read_b128 v[162:165], v209 offset:18432
	ds_read_b128 v[166:169], v209 offset:19456
	ds_read_b128 v[170:173], v209 offset:20480
	ds_read_b128 v[174:177], v209 offset:21504
	ds_read_b128 v[178:181], v209 offset:22528
	ds_read_b128 v[182:185], v209 offset:23552
	global_load_lds_dwordx4 v[202:203], off
	s_mov_b32 m0, s34
	v_lshl_add_u64 v[202:203], s[26:27], 0, v[156:157]
	global_load_lds_dwordx4 v[202:203], off
	s_barrier
	s_waitcnt lgkmcnt(0)
	v_mfma_f32_16x16x32_bf16 v[60:63], v[128:131], v[144:147], 0
	s_setprio 1
	v_mfma_f32_16x16x32_bf16 v[56:59], v[136:139], v[144:147], 0
	v_mfma_f32_16x16x32_bf16 v[52:55], v[128:131], v[162:165], 0
	v_mfma_f32_16x16x32_bf16 v[48:51], v[136:139], v[162:165], 0
	v_mfma_f32_16x16x32_bf16 v[44:47], v[128:131], v[170:173], 0
	v_mfma_f32_16x16x32_bf16 v[40:43], v[136:139], v[170:173], 0
	v_mfma_f32_16x16x32_bf16 v[36:39], v[128:131], v[178:181], 0
	v_mfma_f32_16x16x32_bf16 v[32:35], v[136:139], v[178:181], 0
	v_mfma_f32_16x16x32_bf16 v[60:63], v[132:135], v[148:151], v[60:63]
	v_mfma_f32_16x16x32_bf16 v[56:59], v[140:143], v[148:151], v[56:59]
	v_mfma_f32_16x16x32_bf16 v[52:55], v[132:135], v[166:169], v[52:55]
	v_mfma_f32_16x16x32_bf16 v[48:51], v[140:143], v[166:169], v[48:51]
	v_mfma_f32_16x16x32_bf16 v[44:47], v[132:135], v[174:177], v[44:47]
	v_mfma_f32_16x16x32_bf16 v[40:43], v[140:143], v[174:177], v[40:43]
	v_mfma_f32_16x16x32_bf16 v[36:39], v[132:135], v[182:185], v[36:39]
	s_setprio 0
	v_mfma_f32_16x16x32_bf16 v[32:35], v[140:143], v[182:185], v[32:35]
	s_barrier
; #define PG8_STAGE(bufoff, gbase, voff) do { _Pragma("unroll") for (int _i = 0; _i < 2; ++_i) \
;         __builtin_amdgcn_global_load_lds((const unsigned*)((const char*)(gbase) + (voff)[_i]), (LAS unsigned*)(lds + (bufoff) + ldsw + _i * 8192), 16, 0, 0); } while (0)
; #define PG8_LDA(dst, b, h) do { _Pragma("unroll") for (int m = 0; m < 4; ++m) _Pragma("unroll") for (int k = 0; k < 2; ++k) dst[m][k] = *(const LAS bf16x8*)(lds + PG8_SA(b, h) + aoff + m * 2048 + k * 1024); } while (0)
; #define PG8_LDB(dst, b, h) do { _Pragma("unroll") for (int n = 0; n < 2; ++n) _Pragma("unroll") for (int k = 0; k < 2; ++k) dst[n][k] = *(const LAS bf16x8*)(lds + PG8_SB(b, h) + boff + n * 2048 + k * 1024); } while (0)
; #define PG8_MMA(ai, bj, At, Bt) do { __builtin_amdgcn_s_setprio(1); _Pragma("unroll") for (int m = 0; m < 4; ++m) _Pragma("unroll") for (int n = 0; n < 2; ++n) _Pragma("unroll") for (int k = 0; k < 2; ++k) \
;         acc[ai][bj][m][n] = __builtin_amdgcn_mfma_f32_16x16x32_bf16(Bt[n][k], At[m][k], acc[ai][bj][m][n], 0, 0, 0); __builtin_amdgcn_s_setprio(0); } while (0)
; #define PG8_WAIT_V(n) asm volatile("s_waitcnt vmcnt(" #n ")" ::: "memory")
; #define PG8_WAIT_L(n) asm volatile("s_waitcnt lgkmcnt(" #n ")" ::: "memory")
; #define PG8_BAR __builtin_amdgcn_s_barrier()
; #define PG8_SCHED __builtin_amdgcn_sched_barrier(0)
; template <class Epi>
; __device__ __forceinline__ void gemm_phase(LAS unsigned char* lds, const Gemm g, const StaticOrder& S, const Epi& E) {
;     ...
;             PG8_STAGE(PG8_SB(0, 1), b2 + hstepB, voffB);
;             PG8_WAIT_V(6); PG8_BAR; PG8_MMA(1, 1, At, B1); PG8_BAR;
;             PG8_LDB(B0, 1, 0); PG8_SCHED; PG8_LDA(At, 1, 0); PG8_STAGE(PG8_SA(0, 1), a2 + hstepA, voffA);
;             PG8_WAIT_L(8); PG8_BAR; PG8_WAIT_L(0); PG8_MMA(0, 0, At, B0); PG8_BAR; PG8_SCHED;
;             PG8_LDB(B1, 1, 1); PG8_STAGE(PG8_SB(1, 0), b3, voffB);
;             PG8_BAR; PG8_WAIT_L(0); PG8_MMA(0, 1, At, B1); PG8_BAR;
	s_add_u32 s56, s24, s52
	s_addc_u32 s57, s25, 0
	s_add_i32 s55, s58, s31
	s_mov_b32 m0, s55
	v_lshl_add_u64 v[128:129], s[56:57], 0, v[152:153]
	global_load_lds_dwordx4 v[128:129], off
	s_add_i32 m0, s55, 0x2000
	v_lshl_add_u64 v[128:129], s[56:57], 0, v[156:157]
	global_load_lds_dwordx4 v[128:129], off
	s_waitcnt vmcnt(6)
	s_barrier
	v_mfma_f32_16x16x32_bf16 v[28:31], v[186:189], v[144:147], 0
	s_setprio 1
	v_mfma_f32_16x16x32_bf16 v[24:27], v[194:197], v[144:147], 0
	s_add_i32 s55, 0, 0x18000
	v_add_u32_e32 v140, s55, v207
	v_mfma_f32_16x16x32_bf16 v[20:23], v[186:189], v[162:165], 0
	v_mfma_f32_16x16x32_bf16 v[16:19], v[194:197], v[162:165], 0
	v_mfma_f32_16x16x32_bf16 v[12:15], v[186:189], v[170:173], 0
	v_mfma_f32_16x16x32_bf16 v[8:11], v[194:197], v[170:173], 0
	v_mfma_f32_16x16x32_bf16 v[4:7], v[186:189], v[178:181], 0
	v_mfma_f32_16x16x32_bf16 v[0:3], v[194:197], v[178:181], 0
	v_mfma_f32_16x16x32_bf16 v[28:31], v[190:193], v[148:151], v[28:31]
	v_mfma_f32_16x16x32_bf16 v[24:27], v[198:201], v[148:151], v[24:27]
	v_mfma_f32_16x16x32_bf16 v[20:23], v[190:193], v[166:169], v[20:23]
	v_mfma_f32_16x16x32_bf16 v[16:19], v[198:201], v[166:169], v[16:19]
	v_mfma_f32_16x16x32_bf16 v[12:15], v[190:193], v[174:177], v[12:15]
	v_mfma_f32_16x16x32_bf16 v[8:11], v[198:201], v[174:177], v[8:11]
	v_mfma_f32_16x16x32_bf16 v[4:7], v[190:193], v[182:185], v[4:7]
	s_setprio 0
	v_mfma_f32_16x16x32_bf16 v[0:3], v[198:201], v[182:185], v[0:3]
	s_barrier
	ds_read_b128 v[128:131], v140
	ds_read_b128 v[132:135], v140 offset:1024
	ds_read_b128 v[136:139], v140 offset:2048
	ds_read_b128 v[140:143], v140 offset:3072
	s_add_u32 s26, s26, s52
	s_addc_u32 s27, s27, 0
	s_mov_b32 m0, s35
	v_lshl_add_u64 v[186:187], s[26:27], 0, v[152:153]
	ds_read_b128 v[144:147], v209 offset:32768
	ds_read_b128 v[148:151], v209 offset:33792
	ds_read_b128 v[162:165], v209 offset:34816
	ds_read_b128 v[166:169], v209 offset:35840
	ds_read_b128 v[170:173], v209 offset:36864
	ds_read_b128 v[174:177], v209 offset:37888
	ds_read_b128 v[178:181], v209 offset:38912
	ds_read_b128 v[182:185], v209 offset:39936
	global_load_lds_dwordx4 v[186:187], off
	s_mov_b32 m0, s36
	v_lshl_add_u64 v[186:187], s[26:27], 0, v[156:157]
	global_load_lds_dwordx4 v[186:187], off
	s_waitcnt lgkmcnt(8)
	s_barrier
	s_waitcnt lgkmcnt(0)
	v_mfma_f32_16x16x32_bf16 v[124:127], v[128:131], v[144:147], v[124:127]
	s_setprio 1
	v_mfma_f32_16x16x32_bf16 v[120:123], v[136:139], v[144:147], v[120:123]
	v_mfma_f32_16x16x32_bf16 v[116:119], v[128:131], v[162:165], v[116:119]
	v_mfma_f32_16x16x32_bf16 v[112:115], v[136:139], v[162:165], v[112:115]
	v_mfma_f32_16x16x32_bf16 v[108:111], v[128:131], v[170:173], v[108:111]
	v_mfma_f32_16x16x32_bf16 v[104:107], v[136:139], v[170:173], v[104:107]
	v_mfma_f32_16x16x32_bf16 v[100:103], v[128:131], v[178:181], v[100:103]
	v_mfma_f32_16x16x32_bf16 v[96:99], v[136:139], v[178:181], v[96:99]
	v_mfma_f32_16x16x32_bf16 v[124:127], v[132:135], v[148:151], v[124:127]
	v_mfma_f32_16x16x32_bf16 v[120:123], v[140:143], v[148:151], v[120:123]
	v_mfma_f32_16x16x32_bf16 v[116:119], v[132:135], v[166:169], v[116:119]
	v_mfma_f32_16x16x32_bf16 v[112:115], v[140:143], v[166:169], v[112:115]
	v_mfma_f32_16x16x32_bf16 v[108:111], v[132:135], v[174:177], v[108:111]
	v_mfma_f32_16x16x32_bf16 v[104:107], v[140:143], v[174:177], v[104:107]
	v_mfma_f32_16x16x32_bf16 v[100:103], v[132:135], v[182:185], v[100:103]
	s_setprio 0
	v_mfma_f32_16x16x32_bf16 v[96:99], v[140:143], v[182:185], v[96:99]
	s_barrier
	s_add_i32 s26, 0, 0x1c000
	s_add_u32 s24, s24, 0x4000
	s_addc_u32 s25, s25, 0
	s_add_i32 s27, s55, s31
	v_add_u32_e32 v198, s26, v207
	v_lshl_add_u64 v[202:203], s[24:25], 0, v[152:153]
	s_mov_b32 m0, s27
	ds_read_b128 v[186:189], v198
	ds_read_b128 v[190:193], v198 offset:1024
	ds_read_b128 v[194:197], v198 offset:2048
	ds_read_b128 v[198:201], v198 offset:3072
	global_load_lds_dwordx4 v[202:203], off
	s_add_i32 m0, s27, 0x2000
	v_lshl_add_u64 v[202:203], s[24:25], 0, v[156:157]
	global_load_lds_dwordx4 v[202:203], off
	s_barrier
; #define PG8_STAGE(bufoff, gbase, voff) do { _Pragma("unroll") for (int _i = 0; _i < 2; ++_i) \
;         __builtin_amdgcn_global_load_lds((const unsigned*)((const char*)(gbase) + (voff)[_i]), (LAS unsigned*)(lds + (bufoff) + ldsw + _i * 8192), 16, 0, 0); } while (0)
; #define PG8_LDA(dst, b, h) do { _Pragma("unroll") for (int m = 0; m < 4; ++m) _Pragma("unroll") for (int k = 0; k < 2; ++k) dst[m][k] = *(const LAS bf16x8*)(lds + PG8_SA(b, h) + aoff + m * 2048 + k * 1024); } while (0)
; #define PG8_MMA(ai, bj, At, Bt) do { __builtin_amdgcn_s_setprio(1); _Pragma("unroll") for (int m = 0; m < 4; ++m) _Pragma("unroll") for (int n = 0; n < 2; ++n) _Pragma("unroll") for (int k = 0; k < 2; ++k) \
;         acc[ai][bj][m][n] = __builtin_amdgcn_mfma_f32_16x16x32_bf16(Bt[n][k], At[m][k], acc[ai][bj][m][n], 0, 0, 0); __builtin_amdgcn_s_setprio(0); } while (0)
; #define PG8_WAIT_V(n) asm volatile("s_waitcnt vmcnt(" #n ")" ::: "memory")
; #define PG8_WAIT_L(n) asm volatile("s_waitcnt lgkmcnt(" #n ")" ::: "memory")
; #define PG8_BAR __builtin_amdgcn_s_barrier()
; #define PG8_SCHED __builtin_amdgcn_sched_barrier(0)
; template <class Epi>
; __device__ __forceinline__ void gemm_phase(LAS unsigned char* lds, const Gemm g, const StaticOrder& S, const Epi& E) {
;     ...
;             PG8_BAR; PG8_WAIT_L(0); PG8_MMA(0, 1, At, B1); PG8_BAR;
;             PG8_LDA(At, 1, 1); PG8_STAGE(PG8_SA(1, 0), a3, voffA);
;             PG8_BAR; PG8_WAIT_L(0); PG8_MMA(1, 0, At, B0); PG8_BAR; PG8_SCHED;
;             PG8_STAGE(PG8_SB(1, 1), b3 + hstepB, voffB);
;             PG8_WAIT_V(6); PG8_BAR; PG8_MMA(1, 1, At, B1); PG8_BAR;
;         }
	s_waitcnt lgkmcnt(0)
	v_mfma_f32_16x16x32_bf16 v[92:95], v[186:189], v[144:147], v[92:95]
	s_setprio 1
	v_mfma_f32_16x16x32_bf16 v[88:91], v[194:197], v[144:147], v[88:91]
	s_mov_b32 m0, s38
	v_lshl_add_u64 v[202:203], s[22:23], 0, v[152:153]
	v_mfma_f32_16x16x32_bf16 v[84:87], v[186:189], v[162:165], v[84:87]
	v_mfma_f32_16x16x32_bf16 v[80:83], v[194:197], v[162:165], v[80:83]
	v_mfma_f32_16x16x32_bf16 v[76:79], v[186:189], v[170:173], v[76:79]
	v_mfma_f32_16x16x32_bf16 v[72:75], v[194:197], v[170:173], v[72:75]
	v_mfma_f32_16x16x32_bf16 v[68:71], v[186:189], v[178:181], v[68:71]
	v_mfma_f32_16x16x32_bf16 v[64:67], v[194:197], v[178:181], v[64:67]
	v_mfma_f32_16x16x32_bf16 v[92:95], v[190:193], v[148:151], v[92:95]
	v_mfma_f32_16x16x32_bf16 v[88:91], v[198:201], v[148:151], v[88:91]
	v_mfma_f32_16x16x32_bf16 v[84:87], v[190:193], v[166:169], v[84:87]
	v_mfma_f32_16x16x32_bf16 v[80:83], v[198:201], v[166:169], v[80:83]
	v_mfma_f32_16x16x32_bf16 v[76:79], v[190:193], v[174:177], v[76:79]
	v_mfma_f32_16x16x32_bf16 v[72:75], v[198:201], v[174:177], v[72:75]
	v_mfma_f32_16x16x32_bf16 v[68:71], v[190:193], v[182:185], v[68:71]
	s_setprio 0
	v_mfma_f32_16x16x32_bf16 v[64:67], v[198:201], v[182:185], v[64:67]
	s_barrier
	ds_read_b128 v[144:147], v209 offset:49152
	ds_read_b128 v[148:151], v209 offset:50176
	ds_read_b128 v[162:165], v209 offset:51200
	ds_read_b128 v[166:169], v209 offset:52224
	ds_read_b128 v[170:173], v209 offset:53248
	ds_read_b128 v[174:177], v209 offset:54272
	ds_read_b128 v[178:181], v209 offset:55296
	ds_read_b128 v[182:185], v209 offset:56320
	global_load_lds_dwordx4 v[202:203], off
	s_mov_b32 m0, s39
	v_lshl_add_u64 v[202:203], s[22:23], 0, v[156:157]
	global_load_lds_dwordx4 v[202:203], off
	s_barrier
	s_waitcnt lgkmcnt(0)
	v_mfma_f32_16x16x32_bf16 v[60:63], v[128:131], v[144:147], v[60:63]
	s_setprio 1
	v_mfma_f32_16x16x32_bf16 v[56:59], v[136:139], v[144:147], v[56:59]
	v_mfma_f32_16x16x32_bf16 v[52:55], v[128:131], v[162:165], v[52:55]
	v_mfma_f32_16x16x32_bf16 v[48:51], v[136:139], v[162:165], v[48:51]
	v_mfma_f32_16x16x32_bf16 v[44:47], v[128:131], v[170:173], v[44:47]
	v_mfma_f32_16x16x32_bf16 v[40:43], v[136:139], v[170:173], v[40:43]
	v_mfma_f32_16x16x32_bf16 v[36:39], v[128:131], v[178:181], v[36:39]
	v_mfma_f32_16x16x32_bf16 v[32:35], v[136:139], v[178:181], v[32:35]
	v_mfma_f32_16x16x32_bf16 v[60:63], v[132:135], v[148:151], v[60:63]
	v_mfma_f32_16x16x32_bf16 v[56:59], v[140:143], v[148:151], v[56:59]
	v_mfma_f32_16x16x32_bf16 v[52:55], v[132:135], v[166:169], v[52:55]
	v_mfma_f32_16x16x32_bf16 v[48:51], v[140:143], v[166:169], v[48:51]
	v_mfma_f32_16x16x32_bf16 v[44:47], v[132:135], v[174:177], v[44:47]
	v_mfma_f32_16x16x32_bf16 v[40:43], v[140:143], v[174:177], v[40:43]
	v_mfma_f32_16x16x32_bf16 v[36:39], v[132:135], v[182:185], v[36:39]
	s_setprio 0
	v_mfma_f32_16x16x32_bf16 v[32:35], v[140:143], v[182:185], v[32:35]
	s_barrier
	s_add_u32 s22, s24, s52
	s_addc_u32 s23, s25, 0
	s_add_i32 s24, s26, s31
	s_mov_b32 m0, s24
	v_lshl_add_u64 v[128:129], s[22:23], 0, v[152:153]
	global_load_lds_dwordx4 v[128:129], off
	s_add_i32 m0, s24, 0x2000
	v_lshl_add_u64 v[128:129], s[22:23], 0, v[156:157]
	global_load_lds_dwordx4 v[128:129], off
	s_waitcnt vmcnt(6)
	s_barrier
	v_mfma_f32_16x16x32_bf16 v[28:31], v[186:189], v[144:147], v[28:31]
	s_setprio 1
	v_mfma_f32_16x16x32_bf16 v[24:27], v[194:197], v[144:147], v[24:27]
	s_add_u32 s4, s4, 0x8000
	s_addc_u32 s5, s5, 0
	s_add_u32 s50, s50, 0x8000
	s_addc_u32 s51, s51, 0
	v_mfma_f32_16x16x32_bf16 v[20:23], v[186:189], v[162:165], v[20:23]
	v_mfma_f32_16x16x32_bf16 v[16:19], v[194:197], v[162:165], v[16:19]
	v_mfma_f32_16x16x32_bf16 v[12:15], v[186:189], v[170:173], v[12:15]
	v_mfma_f32_16x16x32_bf16 v[8:11], v[194:197], v[170:173], v[8:11]
	v_mfma_f32_16x16x32_bf16 v[4:7], v[186:189], v[178:181], v[4:7]
	v_mfma_f32_16x16x32_bf16 v[0:3], v[194:197], v[178:181], v[0:3]
	v_mfma_f32_16x16x32_bf16 v[28:31], v[190:193], v[148:151], v[28:31]
	v_mfma_f32_16x16x32_bf16 v[24:27], v[198:201], v[148:151], v[24:27]
	v_mfma_f32_16x16x32_bf16 v[20:23], v[190:193], v[166:169], v[20:23]
	v_mfma_f32_16x16x32_bf16 v[16:19], v[198:201], v[166:169], v[16:19]
	v_mfma_f32_16x16x32_bf16 v[12:15], v[190:193], v[174:177], v[12:15]
	v_mfma_f32_16x16x32_bf16 v[8:11], v[198:201], v[174:177], v[8:11]
	v_mfma_f32_16x16x32_bf16 v[4:7], v[190:193], v[182:185], v[4:7]
	s_cmp_ge_u32 s54, s28
	s_mov_b32 s22, s54
	s_setprio 0
	v_mfma_f32_16x16x32_bf16 v[0:3], v[198:201], v[182:185], v[0:3]
	s_barrier
	s_cbranch_scc0 .LBB0_187
	s_branch .Lpeel_done_187

;     __device__ __forceinline__ void operator()(const f32x4 (&acc)[2][2][4][2], const Unit& u, int wr, int wc, int fr, int fq) const {
;         const int row0 = u.pm * BM + wr * 64 + fr, col0 = u.pn * BM + wc * 32 + 8 * fq;
;         const float* gb = gate + (size_t)(row0 >> 12) * (6 * DM);
;         const bool ln = stats != nullptr;
;         constexpr int GB[4] = {0, 4, 8, 16};
;         f32x2 st[4];
; #pragma unroll
;         for (int grp = 0; grp < 3; ++grp) {
;             u32x4 xv[8]; f32x4 cg[2][2], cl[2][2], cb[2][2];
;             if (grp == 0 || grp == 2) {
; #pragma unroll
;                 for (int m = 0; m < 4; ++m) st[m] = ln ? *(const f32x2*)(stats + 2 * (row0 + (grp ? HALF : 0) + m * 16)) : (f32x2){0.f, 1.f};
.Lpeel_done_187:
	s_lshl_b32 s22, s49, 8
	s_add_i32 s22, s22, s37
	v_or_b32_e32 v162, s22, v206
	v_lshlrev_b32_e32 v170, 1, v162
	v_cndmask_b32_e64 v128, 0, 1, s[12:13]
	v_mov_b32_e32 v182, 1.0
	v_mov_b32_e32 v184, 0
	v_cmp_ne_u32_e64 s[4:5], 1, v128
	s_andn2_b64 vcc, exec, s[12:13]
	v_ashrrev_i32_e32 v171, 31, v170
	v_mov_b32_e32 v192, 0
	v_mov_b32_e32 v194, 1.0
	s_cbranch_vccnz .LBB0_190
	v_lshl_add_u64 v[128:129], v[170:171], 2, s[14:15]
	global_load_dwordx2 v[192:193], v[128:129], off
	s_waitcnt vmcnt(0)
	v_mov_b32_e32 v194, v193

; #define PG8_STAGE(bufoff, gbase, voff) do { _Pragma("unroll") for (int _i = 0; _i < 2; ++_i) \
;         __builtin_amdgcn_global_load_lds((const unsigned*)((const char*)(gbase) + (voff)[_i]), (LAS unsigned*)(lds + (bufoff) + ldsw + _i * 8192), 16, 0, 0); } while (0)
; #define PG8_LDA(dst, b, h) do { _Pragma("unroll") for (int m = 0; m < 4; ++m) _Pragma("unroll") for (int k = 0; k < 2; ++k) dst[m][k] = *(const LAS bf16x8*)(lds + PG8_SA(b, h) + aoff + m * 2048 + k * 1024); } while (0)
; #define PG8_LDB(dst, b, h) do { _Pragma("unroll") for (int n = 0; n < 2; ++n) _Pragma("unroll") for (int k = 0; k < 2; ++k) dst[n][k] = *(const LAS bf16x8*)(lds + PG8_SB(b, h) + boff + n * 2048 + k * 1024); } while (0)
; #define PG8_BAR __builtin_amdgcn_s_barrier()
; template <class Epi>
; __device__ __forceinline__ void gemm_phase(LAS unsigned char* lds, const Gemm g, const StaticOrder& S, const Epi& E) {
;     ...
;         for (int t = 0; t < nt; t += 2) {
;             const bool last = (t == nt - 2);
;             const char* a1 = cA + (size_t)(t + 1) * kstep;
;             const char* a2 = last ? nA : cA + (size_t)(t + 2) * kstep; const char* b2 = last ? nB : cB + (size_t)(t + 2) * kstep;
;             const char* a3 = a2 + kstep; const char* b3 = b2 + kstep;
;             PG8_LDB(B0, 0, 0); PG8_SCHED; PG8_LDA(At, 0, 0); PG8_STAGE(PG8_SA(1, 1), a1 + hstepA, voffA);
;             PG8_WAIT_L(8); PG8_BAR; PG8_WAIT_L(0); PG8_MMA(0, 0, At, B0); PG8_BAR; PG8_SCHED;
;             PG8_LDB(B1, 0, 1); PG8_STAGE(PG8_SB(0, 0), b2, voffB);
;             PG8_BAR; PG8_WAIT_L(0); PG8_MMA(0, 1, At, B1); PG8_BAR;
;             PG8_LDA(At, 0, 1); PG8_STAGE(PG8_SA(0, 0), a2, voffA);
;             PG8_BAR; PG8_WAIT_L(0); PG8_MMA(1, 0, At, B0); PG8_BAR; PG8_SCHED;
;             PG8_STAGE(PG8_SB(0, 1), b2 + hstepB, voffB);
;             PG8_WAIT_V(6); PG8_BAR; PG8_MMA(1, 1, At, B1); PG8_BAR;
;             PG8_LDB(B0, 1, 0); PG8_SCHED; PG8_LDA(At, 1, 0); PG8_STAGE(PG8_SA(0, 1), a2 + hstepA, voffA);
;             PG8_WAIT_L(8); PG8_BAR; PG8_WAIT_L(0); PG8_MMA(0, 0, At, B0); PG8_BAR; PG8_SCHED;
;     ...
; #pragma unroll
;         for (int a = 0; a < 2; ++a)
; #pragma unroll
;             for (int b = 0; b < 2; ++b)
; #pragma unroll
;                 for (int m = 0; m < 4; ++m)
; #pragma unroll
;                     for (int n = 0; n < 2; ++n) acc[a][b][m][n] = (f32x4){0.f, 0.f, 0.f, 0.f};
.LBB0_246:
	s_ashr_i32 s5, s4, 31
	v_cmp_lt_i64_e32 vcc, s[6:7], v[154:155]
	s_lshl_b64 s[6:7], s[4:5], 20
	v_readlane_b32 s8, v252, 53
	v_readlane_b32 s9, v252, 54
	s_add_u32 s6, s8, s6
	s_addc_u32 s7, s9, s7
	s_and_b64 s[8:9], vcc, exec
	s_cselect_b32 s5, s7, s13
	s_cselect_b32 s11, s6, s12
	s_ashr_i32 s3, s2, 31
	s_lshl_b64 s[8:9], s[2:3], 20
	s_add_u32 s8, s21, s8
	s_addc_u32 s9, s22, s9
	s_and_b64 s[16:17], vcc, exec
	s_cselect_b32 s3, s9, s15
	s_cselect_b32 s35, s8, s14
	s_add_u32 s12, s12, 0x84000
	s_addc_u32 s13, s13, 0
	s_add_u32 s36, s14, 0x8000
	s_addc_u32 s37, s15, 0
	s_mov_b32 s38, -2
	s_add_u32 s14, s12, 0xfff84000
	s_addc_u32 s15, s13, -1
	s_cmp_eq_u32 s38, 28
	s_cselect_b32 s18, s11, s14
	s_cselect_b32 s19, s5, s15
	s_cselect_b32 s14, s35, s36
	s_cselect_b32 s15, s3, s37
	s_add_u32 s16, s18, 0x4000
	s_addc_u32 s17, s19, 0
	s_add_i32 s39, 0, 0x10000
	v_add_u32_e32 v140, s39, v170
	ds_read_b128 v[128:131], v140
	ds_read_b128 v[132:135], v140 offset:1024
	ds_read_b128 v[136:139], v140 offset:2048
	ds_read_b128 v[140:143], v140 offset:3072
	v_lshl_add_u64 v[194:195], s[12:13], 0, v[156:157]
	s_add_i32 m0, s25, 0xc000
	ds_read_b128 v[144:147], v172
	ds_read_b128 v[148:151], v172 offset:1024
	ds_read_b128 v[166:169], v172 offset:2048
	ds_read_b128 v[174:177], v172 offset:3072
	ds_read_b128 v[178:181], v172 offset:4096
	ds_read_b128 v[182:185], v172 offset:5120
	ds_read_b128 v[186:189], v172 offset:6144
	ds_read_b128 v[190:193], v172 offset:7168
	global_load_lds_dwordx4 v[194:195], off
	s_add_i32 m0, s25, 0xe000
	v_lshl_add_u64 v[194:195], s[12:13], 0, v[158:159]
	global_load_lds_dwordx4 v[194:195], off
	s_waitcnt lgkmcnt(8)
	s_barrier
	s_waitcnt lgkmcnt(0)
	v_mfma_f32_16x16x32_bf16 v[124:127], v[128:131], v[144:147], 0
	s_setprio 1
	v_mfma_f32_16x16x32_bf16 v[120:123], v[136:139], v[144:147], 0
	v_mfma_f32_16x16x32_bf16 v[108:111], v[128:131], v[166:169], 0
	v_mfma_f32_16x16x32_bf16 v[104:107], v[136:139], v[166:169], 0
	v_mfma_f32_16x16x32_bf16 v[92:95], v[128:131], v[178:181], 0
	v_mfma_f32_16x16x32_bf16 v[88:91], v[136:139], v[178:181], 0
	v_mfma_f32_16x16x32_bf16 v[76:79], v[128:131], v[186:189], 0
	v_mfma_f32_16x16x32_bf16 v[72:75], v[136:139], v[186:189], 0
	v_mfma_f32_16x16x32_bf16 v[124:127], v[132:135], v[148:151], v[124:127]
	v_mfma_f32_16x16x32_bf16 v[120:123], v[140:143], v[148:151], v[120:123]
	v_mfma_f32_16x16x32_bf16 v[108:111], v[132:135], v[174:177], v[108:111]
	v_mfma_f32_16x16x32_bf16 v[104:107], v[140:143], v[174:177], v[104:107]
	v_mfma_f32_16x16x32_bf16 v[92:95], v[132:135], v[182:185], v[92:95]
	v_mfma_f32_16x16x32_bf16 v[88:91], v[140:143], v[182:185], v[88:91]
	v_mfma_f32_16x16x32_bf16 v[76:79], v[132:135], v[190:193], v[76:79]
	s_setprio 0
	v_mfma_f32_16x16x32_bf16 v[72:75], v[140:143], v[190:193], v[72:75]
	s_barrier
	s_add_i32 s42, 0, 0x14000
	s_add_i32 s39, s39, s23
	v_add_u32_e32 v152, s42, v170
	v_lshl_add_u64 v[210:211], s[14:15], 0, v[156:157]
	s_mov_b32 m0, s39
	ds_read_b128 v[194:197], v152
	ds_read_b128 v[198:201], v152 offset:1024
	ds_read_b128 v[202:205], v152 offset:2048
	ds_read_b128 v[206:209], v152 offset:3072
	global_load_lds_dwordx4 v[210:211], off
	s_add_i32 m0, s39, 0x2000
	v_lshl_add_u64 v[210:211], s[14:15], 0, v[158:159]
	global_load_lds_dwordx4 v[210:211], off
	s_barrier
	s_waitcnt lgkmcnt(0)
	v_mfma_f32_16x16x32_bf16 v[116:119], v[194:197], v[144:147], 0
	s_setprio 1
	v_mfma_f32_16x16x32_bf16 v[112:115], v[202:205], v[144:147], 0
	s_mov_b32 m0, s25
	v_lshl_add_u64 v[210:211], s[18:19], 0, v[156:157]
	v_mfma_f32_16x16x32_bf16 v[100:103], v[194:197], v[166:169], 0
	v_mfma_f32_16x16x32_bf16 v[96:99], v[202:205], v[166:169], 0
	v_mfma_f32_16x16x32_bf16 v[84:87], v[194:197], v[178:181], 0
	v_mfma_f32_16x16x32_bf16 v[80:83], v[202:205], v[178:181], 0
	v_mfma_f32_16x16x32_bf16 v[68:71], v[194:197], v[186:189], 0
	v_mfma_f32_16x16x32_bf16 v[64:67], v[202:205], v[186:189], 0
	v_mfma_f32_16x16x32_bf16 v[116:119], v[198:201], v[148:151], v[116:119]
	v_mfma_f32_16x16x32_bf16 v[112:115], v[206:209], v[148:151], v[112:115]
	v_mfma_f32_16x16x32_bf16 v[100:103], v[198:201], v[174:177], v[100:103]
	v_mfma_f32_16x16x32_bf16 v[96:99], v[206:209], v[174:177], v[96:99]
	v_mfma_f32_16x16x32_bf16 v[84:87], v[198:201], v[182:185], v[84:87]
	v_mfma_f32_16x16x32_bf16 v[80:83], v[206:209], v[182:185], v[80:83]
	v_mfma_f32_16x16x32_bf16 v[68:71], v[198:201], v[190:193], v[68:71]
	s_setprio 0
	v_mfma_f32_16x16x32_bf16 v[64:67], v[206:209], v[190:193], v[64:67]
	s_barrier
	ds_read_b128 v[144:147], v172 offset:16384
	ds_read_b128 v[148:151], v172 offset:17408
	ds_read_b128 v[166:169], v172 offset:18432
	ds_read_b128 v[174:177], v172 offset:19456
	ds_read_b128 v[178:181], v172 offset:20480
	ds_read_b128 v[182:185], v172 offset:21504
	ds_read_b128 v[186:189], v172 offset:22528
	ds_read_b128 v[190:193], v172 offset:23552
	global_load_lds_dwordx4 v[210:211], off
	s_mov_b32 m0, s26
	v_lshl_add_u64 v[210:211], s[18:19], 0, v[158:159]
	global_load_lds_dwordx4 v[210:211], off
	s_barrier
	s_waitcnt lgkmcnt(0)
	v_mfma_f32_16x16x32_bf16 v[60:63], v[128:131], v[144:147], 0
	s_setprio 1
	v_mfma_f32_16x16x32_bf16 v[56:59], v[136:139], v[144:147], 0
	v_mfma_f32_16x16x32_bf16 v[44:47], v[128:131], v[166:169], 0
	v_mfma_f32_16x16x32_bf16 v[40:43], v[136:139], v[166:169], 0
	v_mfma_f32_16x16x32_bf16 v[28:31], v[128:131], v[178:181], 0
	v_mfma_f32_16x16x32_bf16 v[24:27], v[136:139], v[178:181], 0
	v_mfma_f32_16x16x32_bf16 v[12:15], v[128:131], v[186:189], 0
	v_mfma_f32_16x16x32_bf16 v[8:11], v[136:139], v[186:189], 0
	v_mfma_f32_16x16x32_bf16 v[60:63], v[132:135], v[148:151], v[60:63]
	v_mfma_f32_16x16x32_bf16 v[56:59], v[140:143], v[148:151], v[56:59]
	v_mfma_f32_16x16x32_bf16 v[44:47], v[132:135], v[174:177], v[44:47]
	v_mfma_f32_16x16x32_bf16 v[40:43], v[140:143], v[174:177], v[40:43]
	v_mfma_f32_16x16x32_bf16 v[28:31], v[132:135], v[182:185], v[28:31]
	v_mfma_f32_16x16x32_bf16 v[24:27], v[140:143], v[182:185], v[24:27]
	v_mfma_f32_16x16x32_bf16 v[12:15], v[132:135], v[190:193], v[12:15]
	s_setprio 0
	v_mfma_f32_16x16x32_bf16 v[8:11], v[140:143], v[190:193], v[8:11]
	s_barrier
; #define PG8_STAGE(bufoff, gbase, voff) do { _Pragma("unroll") for (int _i = 0; _i < 2; ++_i) \
;         __builtin_amdgcn_global_load_lds((const unsigned*)((const char*)(gbase) + (voff)[_i]), (LAS unsigned*)(lds + (bufoff) + ldsw + _i * 8192), 16, 0, 0); } while (0)
; #define PG8_LDA(dst, b, h) do { _Pragma("unroll") for (int m = 0; m < 4; ++m) _Pragma("unroll") for (int k = 0; k < 2; ++k) dst[m][k] = *(const LAS bf16x8*)(lds + PG8_SA(b, h) + aoff + m * 2048 + k * 1024); } while (0)
; #define PG8_LDB(dst, b, h) do { _Pragma("unroll") for (int n = 0; n < 2; ++n) _Pragma("unroll") for (int k = 0; k < 2; ++k) dst[n][k] = *(const LAS bf16x8*)(lds + PG8_SB(b, h) + boff + n * 2048 + k * 1024); } while (0)
; #define PG8_MMA(ai, bj, At, Bt) do { __builtin_amdgcn_s_setprio(1); _Pragma("unroll") for (int m = 0; m < 4; ++m) _Pragma("unroll") for (int n = 0; n < 2; ++n) _Pragma("unroll") for (int k = 0; k < 2; ++k) \
;         acc[ai][bj][m][n] = __builtin_amdgcn_mfma_f32_16x16x32_bf16(Bt[n][k], At[m][k], acc[ai][bj][m][n], 0, 0, 0); __builtin_amdgcn_s_setprio(0); } while (0)
; #define PG8_WAIT_V(n) asm volatile("s_waitcnt vmcnt(" #n ")" ::: "memory")
; #define PG8_WAIT_L(n) asm volatile("s_waitcnt lgkmcnt(" #n ")" ::: "memory")
; #define PG8_BAR __builtin_amdgcn_s_barrier()
; #define PG8_SCHED __builtin_amdgcn_sched_barrier(0)
; template <class Epi>
; __device__ __forceinline__ void gemm_phase(LAS unsigned char* lds, const Gemm g, const StaticOrder& S, const Epi& E) {
;     ...
;             PG8_STAGE(PG8_SB(0, 1), b2 + hstepB, voffB);
;             PG8_WAIT_V(6); PG8_BAR; PG8_MMA(1, 1, At, B1); PG8_BAR;
;             PG8_LDB(B0, 1, 0); PG8_SCHED; PG8_LDA(At, 1, 0); PG8_STAGE(PG8_SA(0, 1), a2 + hstepA, voffA);
;             PG8_WAIT_L(8); PG8_BAR; PG8_WAIT_L(0); PG8_MMA(0, 0, At, B0); PG8_BAR; PG8_SCHED;
;             PG8_LDB(B1, 1, 1); PG8_STAGE(PG8_SB(1, 0), b3, voffB);
;             PG8_BAR; PG8_WAIT_L(0); PG8_MMA(0, 1, At, B1); PG8_BAR;
	s_add_u32 s40, s14, 0x80000
	s_addc_u32 s41, s15, 0
	s_add_i32 s39, s42, s23
	s_mov_b32 m0, s39
	v_lshl_add_u64 v[128:129], s[40:41], 0, v[156:157]
	global_load_lds_dwordx4 v[128:129], off
	s_add_i32 m0, s39, 0x2000
	v_lshl_add_u64 v[128:129], s[40:41], 0, v[158:159]
	global_load_lds_dwordx4 v[128:129], off
	s_waitcnt vmcnt(6)
	s_barrier
	v_mfma_f32_16x16x32_bf16 v[52:55], v[194:197], v[144:147], 0
	s_setprio 1
	v_mfma_f32_16x16x32_bf16 v[48:51], v[202:205], v[144:147], 0
	s_add_i32 s39, 0, 0x18000
	v_add_u32_e32 v140, s39, v170
	v_mfma_f32_16x16x32_bf16 v[36:39], v[194:197], v[166:169], 0
	v_mfma_f32_16x16x32_bf16 v[32:35], v[202:205], v[166:169], 0
	v_mfma_f32_16x16x32_bf16 v[20:23], v[194:197], v[178:181], 0
	v_mfma_f32_16x16x32_bf16 v[16:19], v[202:205], v[178:181], 0
	v_mfma_f32_16x16x32_bf16 v[4:7], v[194:197], v[186:189], 0
	v_mfma_f32_16x16x32_bf16 v[0:3], v[202:205], v[186:189], 0
	v_mfma_f32_16x16x32_bf16 v[52:55], v[198:201], v[148:151], v[52:55]
	v_mfma_f32_16x16x32_bf16 v[48:51], v[206:209], v[148:151], v[48:51]
	v_mfma_f32_16x16x32_bf16 v[36:39], v[198:201], v[174:177], v[36:39]
	v_mfma_f32_16x16x32_bf16 v[32:35], v[206:209], v[174:177], v[32:35]
	v_mfma_f32_16x16x32_bf16 v[20:23], v[198:201], v[182:185], v[20:23]
	v_mfma_f32_16x16x32_bf16 v[16:19], v[206:209], v[182:185], v[16:19]
	v_mfma_f32_16x16x32_bf16 v[4:7], v[198:201], v[190:193], v[4:7]
	s_setprio 0
	v_mfma_f32_16x16x32_bf16 v[0:3], v[206:209], v[190:193], v[0:3]
	s_barrier
	ds_read_b128 v[128:131], v140
	ds_read_b128 v[132:135], v140 offset:1024
	ds_read_b128 v[136:139], v140 offset:2048
	ds_read_b128 v[140:143], v140 offset:3072
	s_add_u32 s18, s18, 0x80000
	s_addc_u32 s19, s19, 0
	s_mov_b32 m0, s27
	v_lshl_add_u64 v[194:195], s[18:19], 0, v[156:157]
	ds_read_b128 v[144:147], v172 offset:32768
	ds_read_b128 v[148:151], v172 offset:33792
	ds_read_b128 v[166:169], v172 offset:34816
	ds_read_b128 v[174:177], v172 offset:35840
	ds_read_b128 v[178:181], v172 offset:36864
	ds_read_b128 v[182:185], v172 offset:37888
	ds_read_b128 v[186:189], v172 offset:38912
	ds_read_b128 v[190:193], v172 offset:39936
	global_load_lds_dwordx4 v[194:195], off
	s_mov_b32 m0, s28
	v_lshl_add_u64 v[194:195], s[18:19], 0, v[158:159]
	global_load_lds_dwordx4 v[194:195], off
	s_waitcnt lgkmcnt(8)
	s_barrier
	s_waitcnt lgkmcnt(0)
	v_mfma_f32_16x16x32_bf16 v[124:127], v[128:131], v[144:147], v[124:127]
	s_setprio 1
	v_mfma_f32_16x16x32_bf16 v[120:123], v[136:139], v[144:147], v[120:123]
	v_mfma_f32_16x16x32_bf16 v[108:111], v[128:131], v[166:169], v[108:111]
	v_mfma_f32_16x16x32_bf16 v[104:107], v[136:139], v[166:169], v[104:107]
	v_mfma_f32_16x16x32_bf16 v[92:95], v[128:131], v[178:181], v[92:95]
	v_mfma_f32_16x16x32_bf16 v[88:91], v[136:139], v[178:181], v[88:91]
	v_mfma_f32_16x16x32_bf16 v[76:79], v[128:131], v[186:189], v[76:79]
	v_mfma_f32_16x16x32_bf16 v[72:75], v[136:139], v[186:189], v[72:75]
	v_mfma_f32_16x16x32_bf16 v[124:127], v[132:135], v[148:151], v[124:127]
	v_mfma_f32_16x16x32_bf16 v[120:123], v[140:143], v[148:151], v[120:123]
	v_mfma_f32_16x16x32_bf16 v[108:111], v[132:135], v[174:177], v[108:111]
	v_mfma_f32_16x16x32_bf16 v[104:107], v[140:143], v[174:177], v[104:107]
	v_mfma_f32_16x16x32_bf16 v[92:95], v[132:135], v[182:185], v[92:95]
	v_mfma_f32_16x16x32_bf16 v[88:91], v[140:143], v[182:185], v[88:91]
	v_mfma_f32_16x16x32_bf16 v[76:79], v[132:135], v[190:193], v[76:79]
	s_setprio 0
	v_mfma_f32_16x16x32_bf16 v[72:75], v[140:143], v[190:193], v[72:75]
	s_barrier
	s_add_i32 s40, 0, 0x1c000
	s_add_u32 s18, s14, 0x4000
	s_addc_u32 s19, s15, 0
	s_add_i32 s39, s39, s23
	v_add_u32_e32 v152, s40, v170
	v_lshl_add_u64 v[210:211], s[18:19], 0, v[156:157]
	s_mov_b32 m0, s39
	ds_read_b128 v[194:197], v152
	ds_read_b128 v[198:201], v152 offset:1024
	ds_read_b128 v[202:205], v152 offset:2048
	ds_read_b128 v[206:209], v152 offset:3072
	global_load_lds_dwordx4 v[210:211], off
	s_add_i32 m0, s39, 0x2000
	v_lshl_add_u64 v[210:211], s[18:19], 0, v[158:159]
	global_load_lds_dwordx4 v[210:211], off
	s_barrier
; #define PG8_STAGE(bufoff, gbase, voff) do { _Pragma("unroll") for (int _i = 0; _i < 2; ++_i) \
;         __builtin_amdgcn_global_load_lds((const unsigned*)((const char*)(gbase) + (voff)[_i]), (LAS unsigned*)(lds + (bufoff) + ldsw + _i * 8192), 16, 0, 0); } while (0)
; #define PG8_LDA(dst, b, h) do { _Pragma("unroll") for (int m = 0; m < 4; ++m) _Pragma("unroll") for (int k = 0; k < 2; ++k) dst[m][k] = *(const LAS bf16x8*)(lds + PG8_SA(b, h) + aoff + m * 2048 + k * 1024); } while (0)
; #define PG8_MMA(ai, bj, At, Bt) do { __builtin_amdgcn_s_setprio(1); _Pragma("unroll") for (int m = 0; m < 4; ++m) _Pragma("unroll") for (int n = 0; n < 2; ++n) _Pragma("unroll") for (int k = 0; k < 2; ++k) \
;         acc[ai][bj][m][n] = __builtin_amdgcn_mfma_f32_16x16x32_bf16(Bt[n][k], At[m][k], acc[ai][bj][m][n], 0, 0, 0); __builtin_amdgcn_s_setprio(0); } while (0)
; #define PG8_WAIT_V(n) asm volatile("s_waitcnt vmcnt(" #n ")" ::: "memory")
; #define PG8_WAIT_L(n) asm volatile("s_waitcnt lgkmcnt(" #n ")" ::: "memory")
; #define PG8_BAR __builtin_amdgcn_s_barrier()
; #define PG8_SCHED __builtin_amdgcn_sched_barrier(0)
; template <class Epi>
; __device__ __forceinline__ void gemm_phase(LAS unsigned char* lds, const Gemm g, const StaticOrder& S, const Epi& E) {
;     ...
;             PG8_BAR; PG8_WAIT_L(0); PG8_MMA(0, 1, At, B1); PG8_BAR;
;             PG8_LDA(At, 1, 1); PG8_STAGE(PG8_SA(1, 0), a3, voffA);
;             PG8_BAR; PG8_WAIT_L(0); PG8_MMA(1, 0, At, B0); PG8_BAR; PG8_SCHED;
;             PG8_STAGE(PG8_SB(1, 1), b3 + hstepB, voffB);
;             PG8_WAIT_V(6); PG8_BAR; PG8_MMA(1, 1, At, B1); PG8_BAR;
;         }
	s_waitcnt lgkmcnt(0)
	v_mfma_f32_16x16x32_bf16 v[116:119], v[194:197], v[144:147], v[116:119]
	s_setprio 1
	v_mfma_f32_16x16x32_bf16 v[112:115], v[202:205], v[144:147], v[112:115]
	s_mov_b32 m0, s29
	v_lshl_add_u64 v[210:211], s[16:17], 0, v[156:157]
	v_mfma_f32_16x16x32_bf16 v[100:103], v[194:197], v[166:169], v[100:103]
	v_mfma_f32_16x16x32_bf16 v[96:99], v[202:205], v[166:169], v[96:99]
	v_mfma_f32_16x16x32_bf16 v[84:87], v[194:197], v[178:181], v[84:87]
	v_mfma_f32_16x16x32_bf16 v[80:83], v[202:205], v[178:181], v[80:83]
	v_mfma_f32_16x16x32_bf16 v[68:71], v[194:197], v[186:189], v[68:71]
	v_mfma_f32_16x16x32_bf16 v[64:67], v[202:205], v[186:189], v[64:67]
	v_mfma_f32_16x16x32_bf16 v[116:119], v[198:201], v[148:151], v[116:119]
	v_mfma_f32_16x16x32_bf16 v[112:115], v[206:209], v[148:151], v[112:115]
	v_mfma_f32_16x16x32_bf16 v[100:103], v[198:201], v[174:177], v[100:103]
	v_mfma_f32_16x16x32_bf16 v[96:99], v[206:209], v[174:177], v[96:99]
	v_mfma_f32_16x16x32_bf16 v[84:87], v[198:201], v[182:185], v[84:87]
	v_mfma_f32_16x16x32_bf16 v[80:83], v[206:209], v[182:185], v[80:83]
	v_mfma_f32_16x16x32_bf16 v[68:71], v[198:201], v[190:193], v[68:71]
	s_setprio 0
	v_mfma_f32_16x16x32_bf16 v[64:67], v[206:209], v[190:193], v[64:67]
	s_barrier
	ds_read_b128 v[144:147], v172 offset:49152
	ds_read_b128 v[148:151], v172 offset:50176
	ds_read_b128 v[166:169], v172 offset:51200
	ds_read_b128 v[174:177], v172 offset:52224
	ds_read_b128 v[178:181], v172 offset:53248
	ds_read_b128 v[182:185], v172 offset:54272
	ds_read_b128 v[186:189], v172 offset:55296
	ds_read_b128 v[190:193], v172 offset:56320
	global_load_lds_dwordx4 v[210:211], off
	s_mov_b32 m0, s30
	v_lshl_add_u64 v[210:211], s[16:17], 0, v[158:159]
	global_load_lds_dwordx4 v[210:211], off
	s_barrier
	s_waitcnt lgkmcnt(0)
	v_mfma_f32_16x16x32_bf16 v[60:63], v[128:131], v[144:147], v[60:63]
	s_setprio 1
	v_mfma_f32_16x16x32_bf16 v[56:59], v[136:139], v[144:147], v[56:59]
	v_mfma_f32_16x16x32_bf16 v[44:47], v[128:131], v[166:169], v[44:47]
	v_mfma_f32_16x16x32_bf16 v[40:43], v[136:139], v[166:169], v[40:43]
	v_mfma_f32_16x16x32_bf16 v[28:31], v[128:131], v[178:181], v[28:31]
	v_mfma_f32_16x16x32_bf16 v[24:27], v[136:139], v[178:181], v[24:27]
	v_mfma_f32_16x16x32_bf16 v[12:15], v[128:131], v[186:189], v[12:15]
	v_mfma_f32_16x16x32_bf16 v[8:11], v[136:139], v[186:189], v[8:11]
	v_mfma_f32_16x16x32_bf16 v[60:63], v[132:135], v[148:151], v[60:63]
	v_mfma_f32_16x16x32_bf16 v[56:59], v[140:143], v[148:151], v[56:59]
	v_mfma_f32_16x16x32_bf16 v[44:47], v[132:135], v[174:177], v[44:47]
	v_mfma_f32_16x16x32_bf16 v[40:43], v[140:143], v[174:177], v[40:43]
	v_mfma_f32_16x16x32_bf16 v[28:31], v[132:135], v[182:185], v[28:31]
	v_mfma_f32_16x16x32_bf16 v[24:27], v[140:143], v[182:185], v[24:27]
	v_mfma_f32_16x16x32_bf16 v[12:15], v[132:135], v[190:193], v[12:15]
	s_setprio 0
	v_mfma_f32_16x16x32_bf16 v[8:11], v[140:143], v[190:193], v[8:11]
	s_barrier
	s_add_u32 s14, s14, 0x84000
	s_addc_u32 s15, s15, 0
	s_add_i32 s16, s40, s23
	s_mov_b32 m0, s16
	v_lshl_add_u64 v[128:129], s[14:15], 0, v[156:157]
	global_load_lds_dwordx4 v[128:129], off
	s_add_i32 m0, s16, 0x2000
	v_lshl_add_u64 v[128:129], s[14:15], 0, v[158:159]
	global_load_lds_dwordx4 v[128:129], off
	s_waitcnt vmcnt(6)
	s_barrier
	v_mfma_f32_16x16x32_bf16 v[52:55], v[194:197], v[144:147], v[52:55]
	s_setprio 1
	v_mfma_f32_16x16x32_bf16 v[48:51], v[202:205], v[144:147], v[48:51]
	s_add_i32 s38, s38, 2
	s_add_u32 s12, s12, 0x8000
	s_addc_u32 s13, s13, 0
	s_add_u32 s36, s36, 0x8000
	s_addc_u32 s37, s37, 0
	v_mfma_f32_16x16x32_bf16 v[36:39], v[194:197], v[166:169], v[36:39]
	v_mfma_f32_16x16x32_bf16 v[32:35], v[202:205], v[166:169], v[32:35]
	v_mfma_f32_16x16x32_bf16 v[20:23], v[194:197], v[178:181], v[20:23]
	v_mfma_f32_16x16x32_bf16 v[16:19], v[202:205], v[178:181], v[16:19]
	v_mfma_f32_16x16x32_bf16 v[4:7], v[194:197], v[186:189], v[4:7]
	v_mfma_f32_16x16x32_bf16 v[0:3], v[202:205], v[186:189], v[0:3]
	v_mfma_f32_16x16x32_bf16 v[52:55], v[198:201], v[148:151], v[52:55]
	v_mfma_f32_16x16x32_bf16 v[48:51], v[206:209], v[148:151], v[48:51]
	v_mfma_f32_16x16x32_bf16 v[36:39], v[198:201], v[174:177], v[36:39]
	v_mfma_f32_16x16x32_bf16 v[32:35], v[206:209], v[174:177], v[32:35]
	v_mfma_f32_16x16x32_bf16 v[20:23], v[198:201], v[182:185], v[20:23]
	v_mfma_f32_16x16x32_bf16 v[16:19], v[206:209], v[182:185], v[16:19]
	v_mfma_f32_16x16x32_bf16 v[4:7], v[198:201], v[190:193], v[4:7]
	s_cmp_gt_u32 s38, 29
	s_setprio 0
	v_mfma_f32_16x16x32_bf16 v[0:3], v[206:209], v[190:193], v[0:3]
	s_barrier
	s_cbranch_scc0 .LBB0_247
	s_branch .Lpeel_done_247

; __device__ __forceinline__ unsigned cvt_pk_bf16(float lo, float hi) { unsigned r; asm volatile("v_cvt_pk_bf16_f32 %0, %1, %2" : "=v"(r) : "v"(lo), "v"(hi)); return r; }
;     __device__ __forceinline__ void operator()(const f32x4 (&acc)[2][2][4][2], const Unit& u, int wr, int wc, int fr, int fq) const {
;         const int row0 = u.pm * BM + wr * 64 + fr, j0 = wc * 16 + 4 * fq, colb = u.pn * BM + j0;
;         if (u.pn < 8) {
;     ...
; #pragma unroll
;             for (int ai = 0; ai < 2; ++ai)
; #pragma unroll
;                 for (int m = 0; m < 4; ++m) {
;                     const int row = row0 + ai * HALF + m * 16;
;                     bf16_t* rowp = O + (size_t)row * DIN + colb;
; #pragma unroll
;                     for (int bj = 0; bj < 2; ++bj) {
;                         const f32x4 o1 = acc[ai][bj][m][0], o2 = acc[ai][bj][m][1];
;                         u32x2 w1, w2; w1.x = cvt_pk_bf16(o1[0], o1[1]); w1.y = cvt_pk_bf16(o1[2], o1[3]); w2.x = cvt_pk_bf16(o2[0], o2[1]); w2.y = cvt_pk_bf16(o2[2], o2[3]);
;                         *(u32x2*)(rowp + bj * HALF) = w1; *(u32x2*)(rowp + bj * HALF + 64) = w2;
;                     }
;                 }
.Lpeel_done_247:
	v_lshl_add_u32 v177, s10, 8, v165
	v_lshl_or_b32 v152, s34, 8, v171
	s_mov_b64 s[10:11], -1
	s_cmp_lt_i32 s34, 8
	v_or_b32_e32 v180, 16, v177
	v_or_b32_e32 v179, 32, v177
	v_or_b32_e32 v178, 48, v177
	v_add_u32_e32 v176, 0x80, v177
	v_add_u32_e32 v175, 0x90, v177
	v_add_u32_e32 v174, 0xa0, v177
	v_add_u32_e32 v173, 0xb0, v177
	s_cbranch_scc1 .LBB0_250
	v_readlane_b32 s10, v252, 57
	v_readlane_b32 s11, v252, 58
	s_movk_i32 s3, 0x3000
	v_lshlrev_b64 v[130:131], 1, v[152:153]
	v_mov_b64_e32 v[128:129], s[10:11]
	v_mad_i64_i32 v[132:133], s[10:11], v177, s3, v[128:129]
	v_lshl_add_u64 v[132:133], v[132:133], 0, v[130:131]
	v_cvt_pk_bf16_f32 v134, v124, v125
	v_cvt_pk_bf16_f32 v135, v126, v127
	v_cvt_pk_bf16_f32 v136, v120, v121
	v_cvt_pk_bf16_f32 v137, v122, v123
	global_store_dwordx2 v[132:133], v[134:135], off
	global_store_dwordx2 v[132:133], v[136:137], off offset:128
	v_cvt_pk_bf16_f32 v134, v116, v117
	v_cvt_pk_bf16_f32 v135, v118, v119
	v_cvt_pk_bf16_f32 v136, v112, v113
	v_cvt_pk_bf16_f32 v137, v114, v115
	global_store_dwordx2 v[132:133], v[134:135], off offset:256
	global_store_dwordx2 v[132:133], v[136:137], off offset:384
	v_mad_i64_i32 v[132:133], s[10:11], v180, s3, v[128:129]
	v_lshl_add_u64 v[132:133], v[132:133], 0, v[130:131]
	v_cvt_pk_bf16_f32 v134, v108, v109
	v_cvt_pk_bf16_f32 v135, v110, v111
	v_cvt_pk_bf16_f32 v136, v104, v105
	v_cvt_pk_bf16_f32 v137, v106, v107
	global_store_dwordx2 v[132:133], v[134:135], off
	global_store_dwordx2 v[132:133], v[136:137], off offset:128
	v_cvt_pk_bf16_f32 v134, v100, v101
	v_cvt_pk_bf16_f32 v135, v102, v103
	v_cvt_pk_bf16_f32 v136, v96, v97
	v_cvt_pk_bf16_f32 v137, v98, v99
	global_store_dwordx2 v[132:133], v[134:135], off offset:256
	global_store_dwordx2 v[132:133], v[136:137], off offset:384
	v_mad_i64_i32 v[132:133], s[10:11], v179, s3, v[128:129]
	v_lshl_add_u64 v[132:133], v[132:133], 0, v[130:131]
	v_cvt_pk_bf16_f32 v134, v92, v93
	v_cvt_pk_bf16_f32 v135, v94, v95
	v_cvt_pk_bf16_f32 v136, v88, v89
	v_cvt_pk_bf16_f32 v137, v90, v91
	global_store_dwordx2 v[132:133], v[134:135], off
	global_store_dwordx2 v[132:133], v[136:137], off offset:128
	v_cvt_pk_bf16_f32 v134, v84, v85
	v_cvt_pk_bf16_f32 v135, v86, v87
	v_cvt_pk_bf16_f32 v136, v80, v81
	v_cvt_pk_bf16_f32 v137, v82, v83
	global_store_dwordx2 v[132:133], v[134:135], off offset:256
	global_store_dwordx2 v[132:133], v[136:137], off offset:384
	v_mad_i64_i32 v[132:133], s[10:11], v178, s3, v[128:129]
	v_lshl_add_u64 v[132:133], v[132:133], 0, v[130:131]
	v_cvt_pk_bf16_f32 v134, v76, v77
	v_cvt_pk_bf16_f32 v135, v78, v79
	v_cvt_pk_bf16_f32 v136, v72, v73
	v_cvt_pk_bf16_f32 v137, v74, v75
	global_store_dwordx2 v[132:133], v[134:135], off
	global_store_dwordx2 v[132:133], v[136:137], off offset:128
	v_cvt_pk_bf16_f32 v134, v68, v69
	v_cvt_pk_bf16_f32 v135, v70, v71
	v_cvt_pk_bf16_f32 v136, v64, v65
	v_cvt_pk_bf16_f32 v137, v66, v67
	global_store_dwordx2 v[132:133], v[134:135], off offset:256
	global_store_dwordx2 v[132:133], v[136:137], off offset:384
	v_mad_i64_i32 v[132:133], s[10:11], v176, s3, v[128:129]
	v_lshl_add_u64 v[132:133], v[132:133], 0, v[130:131]
	v_cvt_pk_bf16_f32 v134, v60, v61
	v_cvt_pk_bf16_f32 v135, v62, v63
	v_cvt_pk_bf16_f32 v136, v56, v57
	v_cvt_pk_bf16_f32 v137, v58, v59
	global_store_dwordx2 v[132:133], v[134:135], off
	global_store_dwordx2 v[132:133], v[136:137], off offset:128
	v_cvt_pk_bf16_f32 v134, v52, v53
	v_cvt_pk_bf16_f32 v135, v54, v55
	v_cvt_pk_bf16_f32 v136, v48, v49
	v_cvt_pk_bf16_f32 v137, v50, v51
	global_store_dwordx2 v[132:133], v[134:135], off offset:256
	global_store_dwordx2 v[132:133], v[136:137], off offset:384
	v_mad_i64_i32 v[132:133], s[10:11], v175, s3, v[128:129]
	v_lshl_add_u64 v[132:133], v[132:133], 0, v[130:131]
	v_cvt_pk_bf16_f32 v134, v44, v45
	v_cvt_pk_bf16_f32 v135, v46, v47
	v_cvt_pk_bf16_f32 v136, v40, v41
	v_cvt_pk_bf16_f32 v137, v42, v43
	global_store_dwordx2 v[132:133], v[134:135], off
	global_store_dwordx2 v[132:133], v[136:137], off offset:128
	v_cvt_pk_bf16_f32 v134, v36, v37
	v_cvt_pk_bf16_f32 v135, v38, v39
	v_cvt_pk_bf16_f32 v136, v32, v33
	v_cvt_pk_bf16_f32 v137, v34, v35
	global_store_dwordx2 v[132:133], v[134:135], off offset:256
	global_store_dwordx2 v[132:133], v[136:137], off offset:384
	v_mad_i64_i32 v[132:133], s[10:11], v174, s3, v[128:129]
	v_lshl_add_u64 v[132:133], v[132:133], 0, v[130:131]
	v_cvt_pk_bf16_f32 v134, v28, v29
	v_cvt_pk_bf16_f32 v135, v30, v31
	v_cvt_pk_bf16_f32 v136, v24, v25
	v_cvt_pk_bf16_f32 v137, v26, v27
	global_store_dwordx2 v[132:133], v[134:135], off
	global_store_dwordx2 v[132:133], v[136:137], off offset:128
	v_cvt_pk_bf16_f32 v134, v20, v21
	v_cvt_pk_bf16_f32 v135, v22, v23
	v_mad_i64_i32 v[128:129], s[10:11], v173, s3, v[128:129]
	v_cvt_pk_bf16_f32 v136, v16, v17
	v_cvt_pk_bf16_f32 v137, v18, v19
	global_store_dwordx2 v[132:133], v[134:135], off offset:256
	global_store_dwordx2 v[132:133], v[136:137], off offset:384
	v_lshl_add_u64 v[128:129], v[128:129], 0, v[130:131]
	v_cvt_pk_bf16_f32 v130, v12, v13
	v_cvt_pk_bf16_f32 v131, v14, v15
	v_cvt_pk_bf16_f32 v132, v8, v9
	v_cvt_pk_bf16_f32 v133, v10, v11
	s_mov_b64 s[10:11], 0
	global_store_dwordx2 v[128:129], v[130:131], off
	global_store_dwordx2 v[128:129], v[132:133], off offset:128
	v_cvt_pk_bf16_f32 v130, v4, v5
	v_cvt_pk_bf16_f32 v131, v6, v7
	v_cvt_pk_bf16_f32 v132, v0, v1
	v_cvt_pk_bf16_f32 v133, v2, v3
